# all four K=2048 GEMM K-loops (in-proj, DFT, out-proj, scores) rewritten as n-major software-pipelined streams with counted waits and early LDS-DMA issue
# speedup vs baseline: 1.0151x; 1.0067x over previous
.LBB0_261:
	s_ashr_i32 s79, s78, 31
	s_lshl_b64 s[2:3], s[78:79], 12
	s_lshl_b32 s78, s14, 8
	s_mov_b64 s[82:83], -1
	s_and_b64 vcc, exec, s[80:81]
	s_cbranch_vccz .LBB0_287
	v_mov_b32_e32 v10, v156
	s_add_u32 s14, s4, s2
	s_addc_u32 s15, s5, s3
	v_ashrrev_i32_e32 v0, 3, v10
	s_add_i32 s80, s78, 0x400
	v_xor_b32_e32 v6, v0, v10
	v_ashrrev_i32_e32 v1, 31, v0
	s_ashr_i32 s81, s80, 31
	v_lshlrev_b64 v[2:3], 12, v[0:1]
	v_lshlrev_b32_e32 v1, 4, v6
	s_lshl_b64 s[80:81], s[80:81], 12
	v_and_b32_e32 v144, 0x70, v1
	v_lshlrev_b32_e32 v1, 4, v10
	s_add_u32 s82, s70, s80
	v_add_u32_e32 v139, 0, v1
	s_addc_u32 s83, s71, s81
	v_lshl_add_u64 v[4:5], s[14:15], 0, v[2:3]
	v_add_u32_e32 v140, s86, v1
	v_readfirstlane_b32 s14, v139
	v_lshl_add_u64 v[4:5], v[4:5], 0, v[144:145]
	v_lshl_add_u64 v[6:7], s[82:83], 0, v[2:3]
	s_mov_b32 m0, s14
	v_readfirstlane_b32 s14, v140
	v_add_u32_e32 v1, 0x2000, v139
	v_lshl_add_u64 v[6:7], v[6:7], 0, v[144:145]
	s_barrier
	global_load_lds_dwordx4 v[4:5], off
	s_mov_b32 m0, s14
	v_readfirstlane_b32 s14, v1
	v_add_u32_e32 v1, 0x2000, v140
	global_load_lds_dwordx4 v[6:7], off
	v_lshl_add_u64 v[8:9], v[4:5], 0, s[50:51]
	s_mov_b32 m0, s14
	v_readfirstlane_b32 s14, v1
	v_add_u32_e32 v1, 0x4000, v139
	global_load_lds_dwordx4 v[8:9], off
	v_lshl_add_u64 v[8:9], v[6:7], 0, s[50:51]
	s_mov_b32 m0, s14
	v_readfirstlane_b32 s14, v1
	v_add_u32_e32 v1, 0x4000, v140
	global_load_lds_dwordx4 v[8:9], off
	v_lshl_add_u64 v[8:9], v[4:5], 0, s[54:55]
	s_mov_b32 m0, s14
	v_readfirstlane_b32 s14, v1
	v_add_u32_e32 v1, 0x6000, v139
	global_load_lds_dwordx4 v[8:9], off
	v_lshl_add_u64 v[8:9], v[6:7], 0, s[54:55]
	s_mov_b32 m0, s14
	v_readfirstlane_b32 s14, v1
	v_add_u32_e32 v1, 0x6000, v140
	global_load_lds_dwordx4 v[8:9], off
	v_lshl_add_u64 v[4:5], v[4:5], 0, s[56:57]
	s_mov_b32 m0, s14
	v_readfirstlane_b32 s14, v1
	global_load_lds_dwordx4 v[4:5], off
	v_lshl_add_u64 v[4:5], v[6:7], 0, s[56:57]
	s_mov_b32 m0, s14
	v_ashrrev_i32_e32 v1, 1, v10
	global_load_lds_dwordx4 v[4:5], off
	v_and_b32_e32 v133, 15, v10
	v_and_b32_e32 v135, 0xffffffc0, v1
	v_bfe_u32 v132, v10, 6, 1
	v_lshrrev_b32_e32 v11, 4, v10
	v_or_b32_e32 v1, v135, v133
	v_and_b32_e32 v6, 7, v10
	v_bfe_u32 v134, v10, 4, 2
	v_lshlrev_b32_e32 v4, 13, v132
	v_lshlrev_b32_e32 v5, 7, v133
	v_lshl_add_u32 v137, v1, 7, 0
	v_bitop3_b32 v1, v11, v6, 3 bitop3:0x6c
	v_bitop3_b32 v0, v0, 7, v10 bitop3:0x48
	v_add3_u32 v136, s86, v4, v5
	v_lshlrev_b32_e32 v141, 4, v1
	v_bitop3_b32 v1, v134, v6, 4 bitop3:0x36
	v_lshl_add_u64 v[4:5], v[2:3], 0, s[2:3]
	v_lshlrev_b32_e32 v144, 4, v0
	v_lshlrev_b32_e32 v138, 4, v1
	v_lshl_add_u64 v[0:1], v[4:5], 0, v[144:145]
	v_lshl_add_u64 v[128:129], s[72:73], 0, v[0:1]
	v_lshl_add_u64 v[0:1], v[2:3], 0, s[80:81]
	s_waitcnt vmcnt(0)
	v_or_b32_e32 v0, v0, v144
	v_lshl_add_u64 v[130:131], s[72:73], 0, v[0:1]
	v_mov_b32_e32 v0, 0
	s_mov_b32 s14, 0
	s_mov_b64 s[80:81], 0
	v_mov_b32_e32 v1, v0
	v_mov_b32_e32 v2, v0
	v_mov_b32_e32 v3, v0
	v_mov_b32_e32 v4, v0
	v_mov_b32_e32 v5, v0
	v_mov_b32_e32 v6, v0
	v_mov_b32_e32 v7, v0
	v_mov_b32_e32 v8, v0
	v_mov_b32_e32 v9, v0
	v_mov_b32_e32 v10, v0
	v_mov_b32_e32 v11, v0
	v_mov_b32_e32 v12, v0
	v_mov_b32_e32 v13, v0
	v_mov_b32_e32 v14, v0
	v_mov_b32_e32 v15, v0
	v_mov_b32_e32 v16, v0
	v_mov_b32_e32 v17, v0
	v_mov_b32_e32 v18, v0
	v_mov_b32_e32 v19, v0
	v_mov_b32_e32 v20, v0
	v_mov_b32_e32 v21, v0
	v_mov_b32_e32 v22, v0
	v_mov_b32_e32 v23, v0
	v_mov_b32_e32 v24, v0
	v_mov_b32_e32 v25, v0
	v_mov_b32_e32 v26, v0
	v_mov_b32_e32 v27, v0
	v_mov_b32_e32 v28, v0
	v_mov_b32_e32 v29, v0
	v_mov_b32_e32 v30, v0
	v_mov_b32_e32 v31, v0
	v_mov_b32_e32 v32, v0
	v_mov_b32_e32 v33, v0
	v_mov_b32_e32 v34, v0
	v_mov_b32_e32 v35, v0
	v_mov_b32_e32 v36, v0
	v_mov_b32_e32 v37, v0
	v_mov_b32_e32 v38, v0
	v_mov_b32_e32 v39, v0
	v_mov_b32_e32 v40, v0
	v_mov_b32_e32 v41, v0
	v_mov_b32_e32 v42, v0
	v_mov_b32_e32 v43, v0
	v_mov_b32_e32 v44, v0
	v_mov_b32_e32 v45, v0
	v_mov_b32_e32 v46, v0
	v_mov_b32_e32 v47, v0
	v_mov_b32_e32 v48, v0
	v_mov_b32_e32 v49, v0
	v_mov_b32_e32 v50, v0
	v_mov_b32_e32 v51, v0
	v_mov_b32_e32 v52, v0
	v_mov_b32_e32 v53, v0
	v_mov_b32_e32 v54, v0
	v_mov_b32_e32 v55, v0
	v_mov_b32_e32 v56, v0
	v_mov_b32_e32 v57, v0
	v_mov_b32_e32 v58, v0
	v_mov_b32_e32 v59, v0
	v_mov_b32_e32 v60, v0
	v_mov_b32_e32 v61, v0
	v_mov_b32_e32 v62, v0
	v_mov_b32_e32 v63, v0
	v_mov_b32_e32 v64, v0
	v_mov_b32_e32 v65, v0
	v_mov_b32_e32 v66, v0
	v_mov_b32_e32 v67, v0
	v_mov_b32_e32 v68, v0
	v_mov_b32_e32 v69, v0
	v_mov_b32_e32 v70, v0
	v_mov_b32_e32 v71, v0
	v_mov_b32_e32 v72, v0
	v_mov_b32_e32 v73, v0
	v_mov_b32_e32 v74, v0
	v_mov_b32_e32 v75, v0
	v_mov_b32_e32 v76, v0
	v_mov_b32_e32 v77, v0
	v_mov_b32_e32 v78, v0
	v_mov_b32_e32 v79, v0
	v_mov_b32_e32 v80, v0
	v_mov_b32_e32 v81, v0
	v_mov_b32_e32 v82, v0
	v_mov_b32_e32 v83, v0
	v_mov_b32_e32 v84, v0
	v_mov_b32_e32 v85, v0
	v_mov_b32_e32 v86, v0
	v_mov_b32_e32 v87, v0
	v_mov_b32_e32 v88, v0
	v_mov_b32_e32 v89, v0
	v_mov_b32_e32 v90, v0
	v_mov_b32_e32 v91, v0
	v_mov_b32_e32 v92, v0
	v_mov_b32_e32 v93, v0
	v_mov_b32_e32 v94, v0
	v_mov_b32_e32 v95, v0
	v_mov_b32_e32 v96, v0
	v_mov_b32_e32 v97, v0
	v_mov_b32_e32 v98, v0
	v_mov_b32_e32 v99, v0
	v_mov_b32_e32 v100, v0
	v_mov_b32_e32 v101, v0
	v_mov_b32_e32 v102, v0
	v_mov_b32_e32 v103, v0
	v_mov_b32_e32 v104, v0
	v_mov_b32_e32 v105, v0
	v_mov_b32_e32 v106, v0
	v_mov_b32_e32 v107, v0
	v_mov_b32_e32 v108, v0
	v_mov_b32_e32 v109, v0
	v_mov_b32_e32 v110, v0
	v_mov_b32_e32 v111, v0
	v_mov_b32_e32 v112, v0
	v_mov_b32_e32 v113, v0
	v_mov_b32_e32 v114, v0
	v_mov_b32_e32 v115, v0
	v_mov_b32_e32 v116, v0
	v_mov_b32_e32 v117, v0
	v_mov_b32_e32 v118, v0
	v_mov_b32_e32 v119, v0
	v_mov_b32_e32 v120, v0
	v_mov_b32_e32 v121, v0
	v_mov_b32_e32 v122, v0
	v_mov_b32_e32 v123, v0
	v_mov_b32_e32 v124, v0
	v_mov_b32_e32 v125, v0
	v_mov_b32_e32 v126, v0
	v_mov_b32_e32 v127, v0
	s_waitcnt vmcnt(0) lgkmcnt(0)
	s_barrier
	v_readfirstlane_b32 s98, v139
	v_readfirstlane_b32 s99, v140
	s_and_b32 s15, s14, 0x8000
	s_xor_b32 s22, s15, 0x8000
	v_add3_u32 v142, v137, v141, s15
	v_add3_u32 v143, v136, v141, s15
	ds_read_b128 v[174:177], v142
	ds_read_b128 v[178:181], v142 offset:2048
	ds_read_b128 v[182:185], v142 offset:4096
	ds_read_b128 v[186:189], v142 offset:6144
	ds_read_b128 v[158:161], v143
	ds_read_b128 v[162:165], v143 offset:2048
	ds_read_b128 v[166:169], v143 offset:4096
	ds_read_b128 v[170:173], v143 offset:6144
	s_add_i32 s100, s98, s22
	s_add_i32 s101, s99, s22
	s_add_u32 s82, s80, 0x7870080
	s_addc_u32 s83, s81, 0
	s_add_i32 m0, s100, 0x0
	v_lshl_add_u64 v[146:147], v[128:129], 0, s[82:83]
	global_load_lds_dwordx4 v[146:147], off
	s_add_u32 s82, s80, s58
	s_addc_u32 s83, s81, s59
	s_add_i32 m0, s101, 0x0
	v_lshl_add_u64 v[146:147], v[130:131], 0, s[82:83]
	global_load_lds_dwordx4 v[146:147], off
	s_add_u32 s82, s80, 0x78b0080
	s_addc_u32 s83, s81, 0
	s_add_i32 m0, s100, 0x2000
	v_lshl_add_u64 v[146:147], v[128:129], 0, s[82:83]
	global_load_lds_dwordx4 v[146:147], off
	s_add_u32 s82, s80, s60
	s_addc_u32 s83, s81, s61
	s_add_i32 m0, s101, 0x2000
	v_lshl_add_u64 v[146:147], v[130:131], 0, s[82:83]
	global_load_lds_dwordx4 v[146:147], off
	s_add_u32 s82, s80, 0x78f0080
	s_addc_u32 s83, s81, 0
	s_add_i32 m0, s100, 0x4000
	v_lshl_add_u64 v[146:147], v[128:129], 0, s[82:83]
	global_load_lds_dwordx4 v[146:147], off
	s_add_u32 s82, s80, s62
	s_addc_u32 s83, s81, s63
	s_add_i32 m0, s101, 0x4000
	v_lshl_add_u64 v[146:147], v[130:131], 0, s[82:83]
	global_load_lds_dwordx4 v[146:147], off
	s_add_u32 s82, s80, 0x7930080
	s_addc_u32 s83, s81, 0
	s_add_i32 m0, s100, 0x6000
	v_lshl_add_u64 v[146:147], v[128:129], 0, s[82:83]
	global_load_lds_dwordx4 v[146:147], off
	s_add_u32 s82, s80, s64
	s_addc_u32 s83, s81, s65
	s_add_i32 m0, s101, 0x6000
	v_lshl_add_u64 v[146:147], v[130:131], 0, s[82:83]
	global_load_lds_dwordx4 v[146:147], off
.LBB0_263:
	s_and_b32 s15, s14, 0x8000
	s_add_i32 s14, s14, 0x8000
	v_add3_u32 v142, v137, v138, s15
	v_add3_u32 v143, v136, v141, s15
	v_add3_u32 v144, v136, v138, s15
	s_waitcnt lgkmcnt(3)
	v_mfma_f32_16x16x32_bf16 v[124:127], v[174:177], v[158:161], v[124:127]
	v_mfma_f32_16x16x32_bf16 v[92:95], v[178:181], v[158:161], v[92:95]
	v_mfma_f32_16x16x32_bf16 v[60:63], v[182:185], v[158:161], v[60:63]
	v_mfma_f32_16x16x32_bf16 v[28:31], v[186:189], v[158:161], v[28:31]
	ds_read_b128 v[158:161], v143 offset:16384
	ds_read_b128 v[190:193], v142
	s_waitcnt lgkmcnt(4)
	v_mfma_f32_16x16x32_bf16 v[120:123], v[174:177], v[162:165], v[120:123]
	v_mfma_f32_16x16x32_bf16 v[88:91], v[178:181], v[162:165], v[88:91]
	v_mfma_f32_16x16x32_bf16 v[56:59], v[182:185], v[162:165], v[56:59]
	v_mfma_f32_16x16x32_bf16 v[24:27], v[186:189], v[162:165], v[24:27]
	ds_read_b128 v[162:165], v143 offset:18432
	ds_read_b128 v[194:197], v142 offset:2048
	s_waitcnt lgkmcnt(5)
	v_mfma_f32_16x16x32_bf16 v[116:119], v[174:177], v[166:169], v[116:119]
	v_mfma_f32_16x16x32_bf16 v[84:87], v[178:181], v[166:169], v[84:87]
	v_mfma_f32_16x16x32_bf16 v[52:55], v[182:185], v[166:169], v[52:55]
	v_mfma_f32_16x16x32_bf16 v[20:23], v[186:189], v[166:169], v[20:23]
	ds_read_b128 v[166:169], v143 offset:20480
	ds_read_b128 v[198:201], v142 offset:4096
	s_waitcnt lgkmcnt(6)
	v_mfma_f32_16x16x32_bf16 v[112:115], v[174:177], v[170:173], v[112:115]
	v_mfma_f32_16x16x32_bf16 v[80:83], v[178:181], v[170:173], v[80:83]
	v_mfma_f32_16x16x32_bf16 v[48:51], v[182:185], v[170:173], v[48:51]
	v_mfma_f32_16x16x32_bf16 v[16:19], v[186:189], v[170:173], v[16:19]
	ds_read_b128 v[170:173], v143 offset:22528
	ds_read_b128 v[150:153], v142 offset:6144
	s_waitcnt lgkmcnt(7)
	v_mfma_f32_16x16x32_bf16 v[108:111], v[174:177], v[158:161], v[108:111]
	v_mfma_f32_16x16x32_bf16 v[76:79], v[178:181], v[158:161], v[76:79]
	v_mfma_f32_16x16x32_bf16 v[44:47], v[182:185], v[158:161], v[44:47]
	v_mfma_f32_16x16x32_bf16 v[12:15], v[186:189], v[158:161], v[12:15]
	ds_read_b128 v[158:161], v144
	s_waitcnt lgkmcnt(6)
	v_mfma_f32_16x16x32_bf16 v[104:107], v[174:177], v[162:165], v[104:107]
	v_mfma_f32_16x16x32_bf16 v[72:75], v[178:181], v[162:165], v[72:75]
	v_mfma_f32_16x16x32_bf16 v[40:43], v[182:185], v[162:165], v[40:43]
	v_mfma_f32_16x16x32_bf16 v[8:11], v[186:189], v[162:165], v[8:11]
	ds_read_b128 v[162:165], v144 offset:2048
	s_waitcnt lgkmcnt(5)
	v_mfma_f32_16x16x32_bf16 v[100:103], v[174:177], v[166:169], v[100:103]
	v_mfma_f32_16x16x32_bf16 v[68:71], v[178:181], v[166:169], v[68:71]
	v_mfma_f32_16x16x32_bf16 v[36:39], v[182:185], v[166:169], v[36:39]
	v_mfma_f32_16x16x32_bf16 v[4:7], v[186:189], v[166:169], v[4:7]
	ds_read_b128 v[166:169], v144 offset:4096
	s_waitcnt lgkmcnt(4)
	v_mfma_f32_16x16x32_bf16 v[96:99], v[174:177], v[170:173], v[96:99]
	v_mfma_f32_16x16x32_bf16 v[64:67], v[178:181], v[170:173], v[64:67]
	v_mfma_f32_16x16x32_bf16 v[32:35], v[182:185], v[170:173], v[32:35]
	v_mfma_f32_16x16x32_bf16 v[0:3], v[186:189], v[170:173], v[0:3]
	ds_read_b128 v[170:173], v144 offset:6144
	s_waitcnt lgkmcnt(3)
	v_mfma_f32_16x16x32_bf16 v[124:127], v[190:193], v[158:161], v[124:127]
	v_mfma_f32_16x16x32_bf16 v[92:95], v[194:197], v[158:161], v[92:95]
	v_mfma_f32_16x16x32_bf16 v[60:63], v[198:201], v[158:161], v[60:63]
	v_mfma_f32_16x16x32_bf16 v[28:31], v[150:153], v[158:161], v[28:31]
	ds_read_b128 v[158:161], v144 offset:16384
	s_waitcnt lgkmcnt(3)
	v_mfma_f32_16x16x32_bf16 v[120:123], v[190:193], v[162:165], v[120:123]
	v_mfma_f32_16x16x32_bf16 v[88:91], v[194:197], v[162:165], v[88:91]
	v_mfma_f32_16x16x32_bf16 v[56:59], v[198:201], v[162:165], v[56:59]
	v_mfma_f32_16x16x32_bf16 v[24:27], v[150:153], v[162:165], v[24:27]
	ds_read_b128 v[162:165], v144 offset:18432
	s_waitcnt lgkmcnt(3)
	v_mfma_f32_16x16x32_bf16 v[116:119], v[190:193], v[166:169], v[116:119]
	v_mfma_f32_16x16x32_bf16 v[84:87], v[194:197], v[166:169], v[84:87]
	v_mfma_f32_16x16x32_bf16 v[52:55], v[198:201], v[166:169], v[52:55]
	v_mfma_f32_16x16x32_bf16 v[20:23], v[150:153], v[166:169], v[20:23]
	ds_read_b128 v[166:169], v144 offset:20480
	s_waitcnt lgkmcnt(3)
	v_mfma_f32_16x16x32_bf16 v[112:115], v[190:193], v[170:173], v[112:115]
	v_mfma_f32_16x16x32_bf16 v[80:83], v[194:197], v[170:173], v[80:83]
	v_mfma_f32_16x16x32_bf16 v[48:51], v[198:201], v[170:173], v[48:51]
	v_mfma_f32_16x16x32_bf16 v[16:19], v[150:153], v[170:173], v[16:19]
	ds_read_b128 v[170:173], v144 offset:22528
	s_waitcnt lgkmcnt(3)
	v_mfma_f32_16x16x32_bf16 v[108:111], v[190:193], v[158:161], v[108:111]
	v_mfma_f32_16x16x32_bf16 v[76:79], v[194:197], v[158:161], v[76:79]
	v_mfma_f32_16x16x32_bf16 v[44:47], v[198:201], v[158:161], v[44:47]
	v_mfma_f32_16x16x32_bf16 v[12:15], v[150:153], v[158:161], v[12:15]
	s_add_u32 s80, s80, 0x80
	s_addc_u32 s81, s81, 0
	s_cmpk_eq_i32 s80, 0xf80
	s_waitcnt vmcnt(0) lgkmcnt(0)
	s_barrier
	s_cbranch_scc1 .Lgemm_263_exit
	s_xor_b32 s22, s15, 0x8000
	v_add3_u32 v142, v137, v141, s22
	v_add3_u32 v143, v136, v141, s22
	ds_read_b128 v[174:177], v142
	ds_read_b128 v[178:181], v142 offset:2048
	ds_read_b128 v[182:185], v142 offset:4096
	ds_read_b128 v[186:189], v142 offset:6144
	ds_read_b128 v[158:161], v143
	s_add_i32 s100, s98, s15
	s_add_i32 s101, s99, s15
	s_add_u32 s82, s80, 0x7870080
	s_addc_u32 s83, s81, 0
	s_add_i32 m0, s100, 0x0
	v_lshl_add_u64 v[146:147], v[128:129], 0, s[82:83]
	global_load_lds_dwordx4 v[146:147], off
	s_add_u32 s82, s80, s58
	s_addc_u32 s83, s81, s59
	s_add_i32 m0, s101, 0x0
	v_lshl_add_u64 v[146:147], v[130:131], 0, s[82:83]
	global_load_lds_dwordx4 v[146:147], off
	v_mfma_f32_16x16x32_bf16 v[104:107], v[190:193], v[162:165], v[104:107]
	v_mfma_f32_16x16x32_bf16 v[72:75], v[194:197], v[162:165], v[72:75]
	v_mfma_f32_16x16x32_bf16 v[40:43], v[198:201], v[162:165], v[40:43]
	v_mfma_f32_16x16x32_bf16 v[8:11], v[150:153], v[162:165], v[8:11]
	ds_read_b128 v[162:165], v143 offset:2048
	s_add_u32 s82, s80, 0x78b0080
	s_addc_u32 s83, s81, 0
	s_add_i32 m0, s100, 0x2000
	v_lshl_add_u64 v[146:147], v[128:129], 0, s[82:83]
	global_load_lds_dwordx4 v[146:147], off
	s_add_u32 s82, s80, s60
	s_addc_u32 s83, s81, s61
	s_add_i32 m0, s101, 0x2000
	v_lshl_add_u64 v[146:147], v[130:131], 0, s[82:83]
	global_load_lds_dwordx4 v[146:147], off
	v_mfma_f32_16x16x32_bf16 v[100:103], v[190:193], v[166:169], v[100:103]
	v_mfma_f32_16x16x32_bf16 v[68:71], v[194:197], v[166:169], v[68:71]
	v_mfma_f32_16x16x32_bf16 v[36:39], v[198:201], v[166:169], v[36:39]
	v_mfma_f32_16x16x32_bf16 v[4:7], v[150:153], v[166:169], v[4:7]
	ds_read_b128 v[166:169], v143 offset:4096
	s_add_u32 s82, s80, 0x78f0080
	s_addc_u32 s83, s81, 0
	s_add_i32 m0, s100, 0x4000
	v_lshl_add_u64 v[146:147], v[128:129], 0, s[82:83]
	global_load_lds_dwordx4 v[146:147], off
	s_add_u32 s82, s80, s62
	s_addc_u32 s83, s81, s63
	s_add_i32 m0, s101, 0x4000
	v_lshl_add_u64 v[146:147], v[130:131], 0, s[82:83]
	global_load_lds_dwordx4 v[146:147], off
	v_mfma_f32_16x16x32_bf16 v[96:99], v[190:193], v[170:173], v[96:99]
	v_mfma_f32_16x16x32_bf16 v[64:67], v[194:197], v[170:173], v[64:67]
	v_mfma_f32_16x16x32_bf16 v[32:35], v[198:201], v[170:173], v[32:35]
	v_mfma_f32_16x16x32_bf16 v[0:3], v[150:153], v[170:173], v[0:3]
	ds_read_b128 v[170:173], v143 offset:6144
	s_add_u32 s82, s80, 0x7930080
	s_addc_u32 s83, s81, 0
	s_add_i32 m0, s100, 0x6000
	v_lshl_add_u64 v[146:147], v[128:129], 0, s[82:83]
	global_load_lds_dwordx4 v[146:147], off
	s_add_u32 s82, s80, s64
	s_addc_u32 s83, s81, s65
	s_add_i32 m0, s101, 0x6000
	v_lshl_add_u64 v[146:147], v[130:131], 0, s[82:83]
	global_load_lds_dwordx4 v[146:147], off
	s_branch .LBB0_263
.Lgemm_263_exit:
	v_mfma_f32_16x16x32_bf16 v[104:107], v[190:193], v[162:165], v[104:107]
	v_mfma_f32_16x16x32_bf16 v[72:75], v[194:197], v[162:165], v[72:75]
	v_mfma_f32_16x16x32_bf16 v[40:43], v[198:201], v[162:165], v[40:43]
	v_mfma_f32_16x16x32_bf16 v[8:11], v[150:153], v[162:165], v[8:11]
	v_mfma_f32_16x16x32_bf16 v[100:103], v[190:193], v[166:169], v[100:103]
	v_mfma_f32_16x16x32_bf16 v[68:71], v[194:197], v[166:169], v[68:71]
	v_mfma_f32_16x16x32_bf16 v[36:39], v[198:201], v[166:169], v[36:39]
	v_mfma_f32_16x16x32_bf16 v[4:7], v[150:153], v[166:169], v[4:7]
	v_mfma_f32_16x16x32_bf16 v[96:99], v[190:193], v[170:173], v[96:99]
	v_mfma_f32_16x16x32_bf16 v[64:67], v[194:197], v[170:173], v[64:67]
	v_mfma_f32_16x16x32_bf16 v[32:35], v[198:201], v[170:173], v[32:35]
	v_mfma_f32_16x16x32_bf16 v[0:3], v[150:153], v[170:173], v[0:3]
	v_add_u32_e32 v139, v137, v141
	ds_read_b128 v[128:131], v139 offset:32768
	v_add_u32_e32 v144, v136, v141
	ds_read_b128 v[140:143], v144 offset:32768
	ds_read_b128 v[150:153], v144 offset:34816
	ds_read_b128 v[158:161], v139 offset:34816
	ds_read_b128 v[162:165], v144 offset:36864
	ds_read_b128 v[166:169], v144 offset:38912
	ds_read_b128 v[170:173], v144 offset:49152
	ds_read_b128 v[174:177], v144 offset:51200
	ds_read_b128 v[178:181], v144 offset:53248
	ds_read_b128 v[182:185], v144 offset:55296
	s_waitcnt lgkmcnt(6)
	v_mfma_f32_16x16x32_bf16 v[92:95], v[158:161], v[140:143], v[92:95]
	s_cmp_gt_i32 s94, 3
	s_mov_b64 s[80:81], -1
	v_mfma_f32_16x16x32_bf16 v[124:127], v[128:131], v[140:143], v[124:127]
	v_mfma_f32_16x16x32_bf16 v[120:123], v[128:131], v[150:153], v[120:123]
	s_waitcnt lgkmcnt(5)
	v_mfma_f32_16x16x32_bf16 v[116:119], v[128:131], v[162:165], v[116:119]
	s_waitcnt lgkmcnt(4)
	v_mfma_f32_16x16x32_bf16 v[112:115], v[128:131], v[166:169], v[112:115]
	s_waitcnt lgkmcnt(3)
	v_mfma_f32_16x16x32_bf16 v[108:111], v[128:131], v[170:173], v[108:111]
	s_waitcnt lgkmcnt(2)
	v_mfma_f32_16x16x32_bf16 v[104:107], v[128:131], v[174:177], v[104:107]
	s_waitcnt lgkmcnt(1)
	v_mfma_f32_16x16x32_bf16 v[100:103], v[128:131], v[178:181], v[100:103]
	s_waitcnt lgkmcnt(0)
	v_mfma_f32_16x16x32_bf16 v[96:99], v[128:131], v[182:185], v[96:99]
	v_mfma_f32_16x16x32_bf16 v[88:91], v[158:161], v[150:153], v[88:91]
	v_mfma_f32_16x16x32_bf16 v[84:87], v[158:161], v[162:165], v[84:87]
	v_mfma_f32_16x16x32_bf16 v[80:83], v[158:161], v[166:169], v[80:83]
	v_mfma_f32_16x16x32_bf16 v[76:79], v[158:161], v[170:173], v[76:79]
	v_mfma_f32_16x16x32_bf16 v[72:75], v[158:161], v[174:177], v[72:75]
	v_mfma_f32_16x16x32_bf16 v[68:71], v[158:161], v[178:181], v[68:71]
	v_mfma_f32_16x16x32_bf16 v[64:67], v[158:161], v[182:185], v[64:67]
	ds_read_b128 v[128:131], v139 offset:36864
	ds_read_b128 v[158:161], v139 offset:38912
	s_waitcnt lgkmcnt(1)
	v_mfma_f32_16x16x32_bf16 v[52:55], v[128:131], v[162:165], v[52:55]
	s_waitcnt lgkmcnt(0)
	v_mfma_f32_16x16x32_bf16 v[162:165], v[158:161], v[162:165], v[20:23]
	s_nop 2
	v_add_u32_e32 v20, v137, v138
	v_mfma_f32_16x16x32_bf16 v[44:47], v[128:131], v[170:173], v[44:47]
	v_mfma_f32_16x16x32_bf16 v[170:173], v[158:161], v[170:173], v[12:15]
	s_nop 2
	ds_read_b128 v[12:15], v20 offset:32768
	v_mfma_f32_16x16x32_bf16 v[186:189], v[128:131], v[178:181], v[36:39]
	v_mfma_f32_16x16x32_bf16 v[178:181], v[158:161], v[178:181], v[4:7]
	s_nop 2
	v_add_u32_e32 v4, v136, v138
	v_mfma_f32_16x16x32_bf16 v[60:63], v[128:131], v[140:143], v[60:63]
	v_mfma_f32_16x16x32_bf16 v[56:59], v[128:131], v[150:153], v[56:59]
	v_mfma_f32_16x16x32_bf16 v[48:51], v[128:131], v[166:169], v[48:51]
	v_mfma_f32_16x16x32_bf16 v[40:43], v[128:131], v[174:177], v[40:43]
	v_mfma_f32_16x16x32_bf16 v[128:131], v[128:131], v[182:185], v[32:35]
	v_mfma_f32_16x16x32_bf16 v[140:143], v[158:161], v[140:143], v[28:31]
	v_mfma_f32_16x16x32_bf16 v[190:193], v[158:161], v[150:153], v[24:27]
	v_mfma_f32_16x16x32_bf16 v[166:169], v[158:161], v[166:169], v[16:19]
	v_mfma_f32_16x16x32_bf16 v[174:177], v[158:161], v[174:177], v[8:11]
	v_mfma_f32_16x16x32_bf16 v[136:139], v[158:161], v[182:185], v[0:3]
	ds_read_b128 v[158:161], v4 offset:32768
	ds_read_b128 v[182:185], v4 offset:34816
	ds_read_b128 v[28:31], v20 offset:34816
	s_waitcnt lgkmcnt(2)
	v_mfma_f32_16x16x32_bf16 v[32:35], v[12:15], v[158:161], v[124:127]
	s_waitcnt lgkmcnt(1)
	v_mfma_f32_16x16x32_bf16 v[36:39], v[12:15], v[182:185], v[120:123]
	s_nop 2
	ds_read_b128 v[120:123], v4 offset:36864
	ds_read_b128 v[124:127], v4 offset:38912
	ds_read_b128 v[194:197], v4 offset:49152
	ds_read_b128 v[198:201], v4 offset:51200
	s_waitcnt lgkmcnt(1)
	v_mfma_f32_16x16x32_bf16 v[0:3], v[12:15], v[194:197], v[108:111]
	s_waitcnt lgkmcnt(0)
	v_mfma_f32_16x16x32_bf16 v[8:11], v[12:15], v[198:201], v[104:107]
	s_nop 2
	ds_read_b128 v[104:107], v4 offset:53248
	ds_read_b128 v[108:111], v4 offset:55296
	v_mfma_f32_16x16x32_bf16 v[116:119], v[12:15], v[120:123], v[116:119]
	v_mfma_f32_16x16x32_bf16 v[112:115], v[12:15], v[124:127], v[112:115]
	s_waitcnt lgkmcnt(1)
	v_mfma_f32_16x16x32_bf16 v[4:7], v[12:15], v[104:107], v[100:103]
	s_waitcnt lgkmcnt(0)
	v_mfma_f32_16x16x32_bf16 v[12:15], v[12:15], v[108:111], v[96:99]
	v_mfma_f32_16x16x32_bf16 v[16:19], v[28:31], v[194:197], v[76:79]
	s_nop 2
	ds_read_b128 v[76:79], v20 offset:38912
	ds_read_b128 v[96:99], v20 offset:36864
	s_waitcnt vmcnt(0)
	s_waitcnt lgkmcnt(0)
	v_mfma_f32_16x16x32_bf16 v[92:95], v[28:31], v[158:161], v[92:95]
	s_barrier
	v_mfma_f32_16x16x32_bf16 v[88:91], v[28:31], v[182:185], v[88:91]
	v_mfma_f32_16x16x32_bf16 v[84:87], v[28:31], v[120:123], v[84:87]
	v_mfma_f32_16x16x32_bf16 v[80:83], v[28:31], v[124:127], v[80:83]
	v_mfma_f32_16x16x32_bf16 v[20:23], v[28:31], v[198:201], v[72:75]
	v_mfma_f32_16x16x32_bf16 v[24:27], v[28:31], v[104:107], v[68:71]
	v_mfma_f32_16x16x32_bf16 v[28:31], v[28:31], v[108:111], v[64:67]
	s_nop 1
	v_mad_u32_u24 v68, v132, s87, 0
	v_lshlrev_b32_e32 v69, 2, v133
	v_mfma_f32_16x16x32_bf16 v[60:63], v[96:99], v[158:161], v[60:63]
	v_lshl_or_b32 v64, v134, 2, v135
	v_mul_lo_u32 v64, v64, s88
	v_add3_u32 v149, v68, v69, v64
	v_mfma_f32_16x16x32_bf16 v[56:59], v[96:99], v[182:185], v[56:59]
	v_add_u32_e32 v150, 0x400, v149
	v_add_u32_e32 v151, 0x2000, v149
	v_add_u32_e32 v152, 0x2400, v149
	v_mfma_f32_16x16x32_bf16 v[52:55], v[96:99], v[120:123], v[52:55]
	v_add_u32_e32 v153, 0x2800, v149
	v_add_u32_e32 v154, 0x4400, v149
	v_add_u32_e32 v155, 0x4800, v149
	v_mfma_f32_16x16x32_bf16 v[48:51], v[96:99], v[124:127], v[48:51]
	ds_write2_b32 v149, v32, v36 offset1:16
	ds_write2_b32 v149, v33, v37 offset0:136 offset1:152
	ds_write2_b32 v150, v34, v38 offset0:16 offset1:32
	ds_write2_b32 v150, v35, v39 offset0:152 offset1:168
	ds_write2_b32 v149, v116, v112 offset0:32 offset1:48
	ds_write2_b32 v149, v117, v113 offset0:168 offset1:184
	ds_write2_b32 v150, v118, v114 offset0:48 offset1:64
	ds_write2_b32 v150, v119, v115 offset0:184 offset1:200
	ds_write2_b32 v151, v92, v88 offset0:128 offset1:144
	ds_write2_b32 v152, v93, v89 offset0:8 offset1:24
	ds_write2_b32 v152, v94, v90 offset0:144 offset1:160
	ds_write2_b32 v153, v95, v91 offset0:24 offset1:40
	ds_write2_b32 v151, v84, v80 offset0:160 offset1:176
	ds_write2_b32 v152, v85, v81 offset0:40 offset1:56
	ds_write2_b32 v152, v86, v82 offset0:176 offset1:192
	ds_write2_b32 v153, v87, v83 offset0:56 offset1:72
	ds_write2_b32 v154, v60, v56 offset1:16
	ds_write2_b32 v154, v61, v57 offset0:136 offset1:152
	v_mfma_f32_16x16x32_bf16 v[64:67], v[76:79], v[158:161], v[140:143]
	ds_write2_b32 v155, v62, v58 offset0:16 offset1:32
	ds_write2_b32 v155, v63, v59 offset0:152 offset1:168
	ds_write2_b32 v154, v52, v48 offset0:32 offset1:48
	v_add_u32_e32 v157, 0x6400, v149
	ds_write2_b32 v154, v53, v49 offset0:168 offset1:184
	ds_write2_b32 v155, v54, v50 offset0:48 offset1:64
	ds_write2_b32 v155, v55, v51 offset0:184 offset1:200
	v_mfma_f32_16x16x32_bf16 v[56:59], v[76:79], v[182:185], v[190:193]
	v_add_u32_e32 v158, 0x6800, v149
	v_add_u32_e32 v159, 0x6c00, v149
	v_mfma_f32_16x16x32_bf16 v[60:63], v[76:79], v[120:123], v[162:165]
	v_mfma_f32_16x16x32_bf16 v[68:71], v[76:79], v[124:127], v[166:169]
	s_nop 3
	ds_write2_b32 v157, v64, v56 offset0:128 offset1:144
	v_mov_b32_e32 v64, v156
	ds_write2_b32 v158, v65, v57 offset0:8 offset1:24
	ds_write2_b32 v158, v66, v58 offset0:144 offset1:160
	ds_write2_b32 v159, v67, v59 offset0:24 offset1:40
	ds_write2_b32 v157, v60, v68 offset0:160 offset1:176
	ds_write2_b32 v158, v61, v69 offset0:40 offset1:56
	ds_write2_b32 v158, v62, v70 offset0:176 offset1:192
	ds_write2_b32 v159, v63, v71 offset0:56 offset1:72
	s_waitcnt lgkmcnt(0)
	s_barrier
	v_mfma_f32_16x16x32_bf16 v[32:35], v[96:99], v[194:197], v[44:47]
	v_ashrrev_i32_e32 v146, 1, v64
	v_and_b32_e32 v160, 1, v64
	v_mul_lo_u32 v64, v146, s88
	v_mul_u32_u24_e32 v65, 0x110, v160
	v_add3_u32 v64, 0, v64, v65
	v_mfma_f32_16x16x32_bf16 v[36:39], v[96:99], v[198:201], v[40:43]
	v_mfma_f32_16x16x32_bf16 v[40:43], v[96:99], v[104:107], v[186:189]
	v_mfma_f32_16x16x32_bf16 v[44:47], v[96:99], v[108:111], v[128:131]
	v_mfma_f32_16x16x32_bf16 v[48:51], v[76:79], v[194:197], v[170:173]
	v_mfma_f32_16x16x32_bf16 v[52:55], v[76:79], v[198:201], v[174:177]
	v_mfma_f32_16x16x32_bf16 v[56:59], v[76:79], v[104:107], v[178:181]
	v_mfma_f32_16x16x32_bf16 v[60:63], v[76:79], v[108:111], v[136:139]
	ds_read_b128 v[124:127], v64
	ds_read_b128 v[120:123], v64 offset:16
	ds_read_b128 v[116:119], v64 offset:32
	ds_read_b128 v[112:115], v64 offset:48
	ds_read_b128 v[108:111], v64 offset:64
	ds_read_b128 v[104:107], v64 offset:80
	ds_read_b128 v[100:103], v64 offset:96
	ds_read_b128 v[96:99], v64 offset:112
	ds_read_b128 v[92:95], v64 offset:128
	ds_read_b128 v[88:91], v64 offset:144
	ds_read_b128 v[84:87], v64 offset:160
	ds_read_b128 v[80:83], v64 offset:176
	ds_read_b128 v[76:79], v64 offset:192
	ds_read_b128 v[72:75], v64 offset:208
	ds_read_b128 v[68:71], v64 offset:224
	ds_read_b128 v[64:67], v64 offset:240
	s_cbranch_scc0 .LBB0_266
	v_add_u32_e32 v128, s9, v146
	v_ashrrev_i32_e32 v129, 31, v128
	v_lshlrev_b64 v[128:129], 11, v[128:129]
	v_lshl_add_u64 v[128:129], s[20:21], 0, v[128:129]
	v_lshl_add_u64 v[128:129], s[66:67], 1, v[128:129]
	v_lshlrev_b32_e32 v144, 7, v160
	v_lshl_add_u64 v[132:133], v[128:129], 0, v[144:145]
	s_waitcnt lgkmcnt(14)
	v_cvt_pk_bf16_f32 v128, v124, v125
	v_cvt_pk_bf16_f32 v129, v126, v127
	v_cvt_pk_bf16_f32 v130, v120, v121
	v_cvt_pk_bf16_f32 v131, v122, v123
	global_store_dwordx4 v[132:133], v[128:131], off
	s_mov_b64 s[80:81], 0
	s_waitcnt lgkmcnt(13)
	v_cvt_pk_bf16_f32 v128, v116, v117
	v_cvt_pk_bf16_f32 v129, v118, v119
	s_waitcnt lgkmcnt(12)
	v_cvt_pk_bf16_f32 v130, v112, v113
	v_cvt_pk_bf16_f32 v131, v114, v115
	global_store_dwordx4 v[132:133], v[128:131], off offset:16
	s_waitcnt lgkmcnt(11)
	s_nop 0
	v_cvt_pk_bf16_f32 v128, v108, v109
	v_cvt_pk_bf16_f32 v129, v110, v111
	s_waitcnt lgkmcnt(10)
	v_cvt_pk_bf16_f32 v130, v104, v105
	v_cvt_pk_bf16_f32 v131, v106, v107
	global_store_dwordx4 v[132:133], v[128:131], off offset:32
	s_waitcnt lgkmcnt(9)
	s_nop 0
	v_cvt_pk_bf16_f32 v128, v100, v101
	v_cvt_pk_bf16_f32 v129, v102, v103
	s_waitcnt lgkmcnt(8)
	v_cvt_pk_bf16_f32 v130, v96, v97
	v_cvt_pk_bf16_f32 v131, v98, v99
	global_store_dwordx4 v[132:133], v[128:131], off offset:48
	s_waitcnt lgkmcnt(7)
	s_nop 0
	v_cvt_pk_bf16_f32 v128, v92, v93
	v_cvt_pk_bf16_f32 v129, v94, v95
	s_waitcnt lgkmcnt(6)
	v_cvt_pk_bf16_f32 v130, v88, v89
	v_cvt_pk_bf16_f32 v131, v90, v91
	global_store_dwordx4 v[132:133], v[128:131], off offset:64
	s_waitcnt lgkmcnt(5)
	s_nop 0
	v_cvt_pk_bf16_f32 v128, v84, v85
	v_cvt_pk_bf16_f32 v129, v86, v87
	s_waitcnt lgkmcnt(4)
	v_cvt_pk_bf16_f32 v130, v80, v81
	v_cvt_pk_bf16_f32 v131, v82, v83
	global_store_dwordx4 v[132:133], v[128:131], off offset:80
	s_waitcnt lgkmcnt(3)
	s_nop 0
	v_cvt_pk_bf16_f32 v128, v76, v77
	v_cvt_pk_bf16_f32 v129, v78, v79
	s_waitcnt lgkmcnt(2)
	v_cvt_pk_bf16_f32 v130, v72, v73
	v_cvt_pk_bf16_f32 v131, v74, v75
	global_store_dwordx4 v[132:133], v[128:131], off offset:96
	s_waitcnt lgkmcnt(1)
	s_nop 0
	v_cvt_pk_bf16_f32 v128, v68, v69
	v_cvt_pk_bf16_f32 v129, v70, v71
	s_waitcnt lgkmcnt(0)
	v_cvt_pk_bf16_f32 v130, v64, v65
	v_cvt_pk_bf16_f32 v131, v66, v67

.LBB0_495:
	s_bitcmp1_b32 s33, 2
	s_cselect_b64 s[60:61], -1, 0
	s_lshl_b32 s62, s33, 10
	s_lshl_b32 s4, s8, 13
	s_and_b32 s70, s62, 0x1000
	s_lshl_b32 s62, s33, 21
	s_bfe_u32 s65, s8, 0x20008
	s_and_b32 s4, s4, 0x600000
	s_ashr_i32 s64, s33, 3
	s_and_b32 s62, s62, 0x600000
	s_add_u32 s62, s18, s62
	s_addc_u32 s63, s19, 0
	s_add_u32 s62, s62, s70
	s_addc_u32 s63, s63, 0
	s_lshl_b32 s66, s64, 8
	v_mov_b32_e32 v10, v156
	s_ashr_i32 s67, s66, 31
	s_lshl_b64 s[66:67], s[66:67], 13
	v_ashrrev_i32_e32 v0, 3, v10
	v_xor_b32_e32 v6, v0, v10
	v_ashrrev_i32_e32 v1, 31, v0
	s_add_u32 s68, s0, s66
	v_lshlrev_b64 v[2:3], 13, v[0:1]
	v_lshlrev_b32_e32 v1, 4, v6
	s_addc_u32 s69, s1, s67
	v_and_b32_e32 v132, 0x70, v1
	v_lshlrev_b32_e32 v1, 4, v10
	s_add_u32 s68, s68, s70
	v_add_u32_e32 v140, 0, v1
	s_addc_u32 s69, s69, 0
	v_lshl_add_u64 v[4:5], s[62:63], 0, v[2:3]
	v_add_u32_e32 v141, s14, v1
	v_readfirstlane_b32 s62, v140
	v_lshl_add_u64 v[4:5], v[4:5], 0, v[132:133]
	v_lshl_add_u64 v[6:7], s[68:69], 0, v[2:3]
	s_mov_b32 m0, s62
	v_readfirstlane_b32 s62, v141
	v_add_u32_e32 v1, 0x2000, v140
	v_lshl_add_u64 v[6:7], v[6:7], 0, v[132:133]
	s_barrier
	global_load_lds_dwordx4 v[4:5], off
	s_mov_b32 m0, s62
	v_readfirstlane_b32 s62, v1
	v_add_u32_e32 v1, 0x2000, v141
	global_load_lds_dwordx4 v[6:7], off
	v_lshl_add_u64 v[8:9], v[4:5], 0, s[6:7]
	s_mov_b32 m0, s62
	v_readfirstlane_b32 s62, v1
	v_add_u32_e32 v1, 0x4000, v140
	global_load_lds_dwordx4 v[8:9], off
	v_lshl_add_u64 v[8:9], v[6:7], 0, s[6:7]
	s_mov_b32 m0, s62
	v_readfirstlane_b32 s62, v1
	v_add_u32_e32 v1, 0x4000, v141
	global_load_lds_dwordx4 v[8:9], off
	v_lshl_add_u64 v[8:9], v[4:5], 0, s[26:27]
	s_mov_b32 m0, s62
	v_readfirstlane_b32 s62, v1
	v_add_u32_e32 v1, 0x6000, v140
	global_load_lds_dwordx4 v[8:9], off
	v_lshl_add_u64 v[8:9], v[6:7], 0, s[26:27]
	s_mov_b32 m0, s62
	v_readfirstlane_b32 s62, v1
	v_add_u32_e32 v1, 0x6000, v141
	global_load_lds_dwordx4 v[8:9], off
	v_lshl_add_u64 v[4:5], v[4:5], 0, s[36:37]
	s_mov_b32 m0, s62
	v_readfirstlane_b32 s62, v1
	global_load_lds_dwordx4 v[4:5], off
	v_lshl_add_u64 v[4:5], v[6:7], 0, s[36:37]
	s_mov_b32 m0, s62
	v_ashrrev_i32_e32 v1, 1, v10
	global_load_lds_dwordx4 v[4:5], off
	v_and_b32_e32 v135, 15, v10
	v_and_b32_e32 v136, 0xffffffc0, v1
	v_lshrrev_b32_e32 v11, 4, v10
	v_or_b32_e32 v1, v136, v135
	v_and_b32_e32 v6, 7, v10
	v_bfe_u32 v134, v10, 6, 1
	v_bfe_u32 v132, v10, 4, 2
	v_lshl_add_u32 v137, v1, 7, 0
	v_bitop3_b32 v1, v11, v6, 3 bitop3:0x6c
	v_lshlrev_b32_e32 v4, 13, v134
	v_lshlrev_b32_e32 v5, 7, v135
	v_lshlrev_b32_e32 v142, 4, v1
	v_bitop3_b32 v1, v132, v6, 4 bitop3:0x36
	v_bitop3_b32 v0, v0, 7, v10 bitop3:0x48
	s_waitcnt vmcnt(0)
	v_add3_u32 v139, s14, v4, v5
	v_lshlrev_b32_e32 v138, 4, v1
	v_lshl_add_u64 v[4:5], s[4:5], 0, v[2:3]
	v_lshlrev_b32_e32 v6, 4, v0
	v_lshl_add_u64 v[0:1], v[2:3], 0, s[66:67]
	v_or3_b32 v4, v4, s70, v6
	v_or3_b32 v0, v0, s70, v6
	v_lshl_add_u64 v[128:129], s[72:73], 0, v[4:5]
	v_lshl_add_u64 v[130:131], s[72:73], 0, v[0:1]
	s_mov_b64 s[62:63], 0
	s_mov_b32 s4, 0
	v_mov_b32_e32 v20, 0
	v_mov_b32_e32 v21, v133
	v_mov_b32_e32 v22, v133
	v_mov_b32_e32 v23, v133
	v_mov_b32_e32 v100, 0
	v_mov_b32_e32 v101, v133
	v_mov_b32_e32 v102, v133
	v_mov_b32_e32 v103, v133
	v_mov_b32_e32 v0, 0
	v_mov_b32_e32 v1, v133
	v_mov_b32_e32 v2, v133
	v_mov_b32_e32 v3, v133
	v_mov_b32_e32 v32, 0
	v_mov_b32_e32 v33, v133
	v_mov_b32_e32 v34, v133
	v_mov_b32_e32 v35, v133
	v_mov_b32_e32 v36, 0
	v_mov_b32_e32 v37, v133
	v_mov_b32_e32 v38, v133
	v_mov_b32_e32 v39, v133
	v_mov_b32_e32 v40, 0
	v_mov_b32_e32 v41, v133
	v_mov_b32_e32 v42, v133
	v_mov_b32_e32 v43, v133
	v_mov_b32_e32 v44, 0
	v_mov_b32_e32 v45, v133
	v_mov_b32_e32 v46, v133
	v_mov_b32_e32 v47, v133
	v_mov_b32_e32 v48, 0
	v_mov_b32_e32 v49, v133
	v_mov_b32_e32 v50, v133
	v_mov_b32_e32 v51, v133
	v_mov_b32_e32 v4, 0
	v_mov_b32_e32 v5, v133
	v_mov_b32_e32 v6, v133
	v_mov_b32_e32 v7, v133
	v_mov_b32_e32 v52, 0
	v_mov_b32_e32 v53, v133
	v_mov_b32_e32 v54, v133
	v_mov_b32_e32 v55, v133
	v_mov_b32_e32 v8, 0
	v_mov_b32_e32 v9, v133
	v_mov_b32_e32 v10, v133
	v_mov_b32_e32 v11, v133
	v_mov_b32_e32 v56, 0
	v_mov_b32_e32 v57, v133
	v_mov_b32_e32 v58, v133
	v_mov_b32_e32 v59, v133
	v_mov_b32_e32 v60, 0
	v_mov_b32_e32 v61, v133
	v_mov_b32_e32 v62, v133
	v_mov_b32_e32 v63, v133
	v_mov_b32_e32 v64, 0
	v_mov_b32_e32 v65, v133
	v_mov_b32_e32 v66, v133
	v_mov_b32_e32 v67, v133
	v_mov_b32_e32 v68, 0
	v_mov_b32_e32 v69, v133
	v_mov_b32_e32 v70, v133
	v_mov_b32_e32 v71, v133
	v_mov_b32_e32 v72, 0
	v_mov_b32_e32 v73, v133
	v_mov_b32_e32 v74, v133
	v_mov_b32_e32 v75, v133
	v_mov_b32_e32 v12, 0
	v_mov_b32_e32 v13, v133
	v_mov_b32_e32 v14, v133
	v_mov_b32_e32 v15, v133
	v_mov_b32_e32 v76, 0
	v_mov_b32_e32 v77, v133
	v_mov_b32_e32 v78, v133
	v_mov_b32_e32 v79, v133
	v_mov_b32_e32 v16, 0
	v_mov_b32_e32 v17, v133
	v_mov_b32_e32 v18, v133
	v_mov_b32_e32 v19, v133
	v_mov_b32_e32 v80, 0
	v_mov_b32_e32 v81, v133
	v_mov_b32_e32 v82, v133
	v_mov_b32_e32 v83, v133
	v_mov_b32_e32 v84, 0
	v_mov_b32_e32 v85, v133
	v_mov_b32_e32 v86, v133
	v_mov_b32_e32 v87, v133
	v_mov_b32_e32 v88, 0
	v_mov_b32_e32 v89, v133
	v_mov_b32_e32 v90, v133
	v_mov_b32_e32 v91, v133
	v_mov_b32_e32 v92, 0
	v_mov_b32_e32 v93, v133
	v_mov_b32_e32 v94, v133
	v_mov_b32_e32 v95, v133
	v_mov_b32_e32 v96, 0
	v_mov_b32_e32 v97, v133
	v_mov_b32_e32 v98, v133
	v_mov_b32_e32 v99, v133
	v_mov_b32_e32 v24, 0
	v_mov_b32_e32 v25, v133
	v_mov_b32_e32 v26, v133
	v_mov_b32_e32 v27, v133
	v_mov_b32_e32 v104, 0
	v_mov_b32_e32 v105, v133
	v_mov_b32_e32 v106, v133
	v_mov_b32_e32 v107, v133
	v_mov_b32_e32 v28, 0
	v_mov_b32_e32 v29, v133
	v_mov_b32_e32 v30, v133
	v_mov_b32_e32 v31, v133
	v_mov_b32_e32 v108, 0
	v_mov_b32_e32 v109, v133
	v_mov_b32_e32 v110, v133
	v_mov_b32_e32 v111, v133
	v_mov_b32_e32 v112, 0
	v_mov_b32_e32 v113, v133
	v_mov_b32_e32 v114, v133
	v_mov_b32_e32 v115, v133
	v_mov_b32_e32 v116, 0
	v_mov_b32_e32 v117, v133
	v_mov_b32_e32 v118, v133
	v_mov_b32_e32 v119, v133
	v_mov_b32_e32 v120, 0
	v_mov_b32_e32 v121, v133
	v_mov_b32_e32 v122, v133
	v_mov_b32_e32 v123, v133
	v_mov_b32_e32 v124, 0
	v_mov_b32_e32 v125, v133
	v_mov_b32_e32 v126, v133
	v_mov_b32_e32 v127, v133
	s_waitcnt vmcnt(0) lgkmcnt(0)
	s_barrier
	v_readfirstlane_b32 s66, v140
	v_readfirstlane_b32 s67, v141
	s_and_b32 s70, s4, 0x8000
	s_xor_b32 s71, s70, 0x8000
	v_add3_u32 v143, v137, v142, s70
	v_add3_u32 v157, v139, v142, s70
	ds_read_b128 v[174:177], v143
	ds_read_b128 v[178:181], v143 offset:2048
	ds_read_b128 v[182:185], v143 offset:4096
	ds_read_b128 v[144:147], v143 offset:6144
	ds_read_b128 v[158:161], v157
	ds_read_b128 v[162:165], v157 offset:2048
	ds_read_b128 v[166:169], v157 offset:4096
	ds_read_b128 v[170:173], v157 offset:6144
	s_add_i32 s76, s66, s71
	s_add_i32 s77, s67, s71
	s_add_u32 s68, s62, s38
	s_addc_u32 s69, s63, s39
	s_add_i32 m0, s76, 0x0
	v_lshl_add_u64 v[242:243], v[128:129], 0, s[68:69]
	global_load_lds_dwordx4 v[242:243], off
	s_add_u32 s68, s62, s40
	s_addc_u32 s69, s63, s41
	s_add_i32 m0, s77, 0x0
	v_lshl_add_u64 v[242:243], v[130:131], 0, s[68:69]
	global_load_lds_dwordx4 v[242:243], off
	s_add_u32 s68, s62, s44
	s_addc_u32 s69, s63, s45
	s_add_i32 m0, s76, 0x2000
	v_lshl_add_u64 v[242:243], v[128:129], 0, s[68:69]
	global_load_lds_dwordx4 v[242:243], off
	s_add_u32 s68, s62, s48
	s_addc_u32 s69, s63, s49
	s_add_i32 m0, s77, 0x2000
	v_lshl_add_u64 v[242:243], v[130:131], 0, s[68:69]
	global_load_lds_dwordx4 v[242:243], off
	s_add_u32 s68, s62, s50
	s_addc_u32 s69, s63, s51
	s_add_i32 m0, s76, 0x4000
	v_lshl_add_u64 v[242:243], v[128:129], 0, s[68:69]
	global_load_lds_dwordx4 v[242:243], off
	s_add_u32 s68, s62, s54
	s_addc_u32 s69, s63, s55
	s_add_i32 m0, s77, 0x4000
	v_lshl_add_u64 v[242:243], v[130:131], 0, s[68:69]
	global_load_lds_dwordx4 v[242:243], off
	s_add_u32 s68, s62, s56
	s_addc_u32 s69, s63, s57
	s_add_i32 m0, s76, 0x6000
	v_lshl_add_u64 v[242:243], v[128:129], 0, s[68:69]
	global_load_lds_dwordx4 v[242:243], off
	s_add_u32 s68, s62, s58
	s_addc_u32 s69, s63, s59
	s_add_i32 m0, s77, 0x6000
	v_lshl_add_u64 v[242:243], v[130:131], 0, s[68:69]
	global_load_lds_dwordx4 v[242:243], off
.LBB0_496:
	s_and_b32 s70, s4, 0x8000
	s_add_i32 s4, s4, 0x8000
	v_add3_u32 v143, v137, v138, s70
	v_add3_u32 v157, v139, v142, s70
	v_add3_u32 v186, v139, v138, s70
	s_waitcnt lgkmcnt(3)
	v_mfma_f32_16x16x32_bf16 v[124:127], v[174:177], v[158:161], v[124:127]
	v_mfma_f32_16x16x32_bf16 v[96:99], v[178:181], v[158:161], v[96:99]
	v_mfma_f32_16x16x32_bf16 v[72:75], v[182:185], v[158:161], v[72:75]
	v_mfma_f32_16x16x32_bf16 v[48:51], v[144:147], v[158:161], v[48:51]
	ds_read_b128 v[158:161], v157 offset:16384
	ds_read_b128 v[148:151], v143
	s_waitcnt lgkmcnt(4)
	v_mfma_f32_16x16x32_bf16 v[120:123], v[174:177], v[162:165], v[120:123]
	v_mfma_f32_16x16x32_bf16 v[92:95], v[178:181], v[162:165], v[92:95]
	v_mfma_f32_16x16x32_bf16 v[68:71], v[182:185], v[162:165], v[68:71]
	v_mfma_f32_16x16x32_bf16 v[44:47], v[144:147], v[162:165], v[44:47]
	ds_read_b128 v[162:165], v157 offset:18432
	ds_read_b128 v[152:155], v143 offset:2048
	s_waitcnt lgkmcnt(5)
	v_mfma_f32_16x16x32_bf16 v[116:119], v[174:177], v[166:169], v[116:119]
	v_mfma_f32_16x16x32_bf16 v[88:91], v[178:181], v[166:169], v[88:91]
	v_mfma_f32_16x16x32_bf16 v[64:67], v[182:185], v[166:169], v[64:67]
	v_mfma_f32_16x16x32_bf16 v[40:43], v[144:147], v[166:169], v[40:43]
	ds_read_b128 v[166:169], v157 offset:20480
	ds_read_b128 v[244:247], v143 offset:4096
	s_waitcnt lgkmcnt(6)
	v_mfma_f32_16x16x32_bf16 v[112:115], v[174:177], v[170:173], v[112:115]
	v_mfma_f32_16x16x32_bf16 v[84:87], v[178:181], v[170:173], v[84:87]
	v_mfma_f32_16x16x32_bf16 v[60:63], v[182:185], v[170:173], v[60:63]
	v_mfma_f32_16x16x32_bf16 v[36:39], v[144:147], v[170:173], v[36:39]
	ds_read_b128 v[170:173], v157 offset:22528
	ds_read_b128 v[248:251], v143 offset:6144
	s_waitcnt lgkmcnt(7)
	v_mfma_f32_16x16x32_bf16 v[108:111], v[174:177], v[158:161], v[108:111]
	v_mfma_f32_16x16x32_bf16 v[80:83], v[178:181], v[158:161], v[80:83]
	v_mfma_f32_16x16x32_bf16 v[56:59], v[182:185], v[158:161], v[56:59]
	v_mfma_f32_16x16x32_bf16 v[32:35], v[144:147], v[158:161], v[32:35]
	ds_read_b128 v[158:161], v186
	s_waitcnt lgkmcnt(6)
	v_mfma_f32_16x16x32_bf16 v[28:31], v[174:177], v[162:165], v[28:31]
	v_mfma_f32_16x16x32_bf16 v[16:19], v[178:181], v[162:165], v[16:19]
	v_mfma_f32_16x16x32_bf16 v[8:11], v[182:185], v[162:165], v[8:11]
	v_mfma_f32_16x16x32_bf16 v[0:3], v[144:147], v[162:165], v[0:3]
	ds_read_b128 v[162:165], v186 offset:2048
	s_waitcnt lgkmcnt(5)
	v_mfma_f32_16x16x32_bf16 v[104:107], v[174:177], v[166:169], v[104:107]
	v_mfma_f32_16x16x32_bf16 v[76:79], v[178:181], v[166:169], v[76:79]
	v_mfma_f32_16x16x32_bf16 v[52:55], v[182:185], v[166:169], v[52:55]
	v_mfma_f32_16x16x32_bf16 v[100:103], v[144:147], v[166:169], v[100:103]
	ds_read_b128 v[166:169], v186 offset:4096
	s_waitcnt lgkmcnt(4)
	v_mfma_f32_16x16x32_bf16 v[24:27], v[174:177], v[170:173], v[24:27]
	v_mfma_f32_16x16x32_bf16 v[12:15], v[178:181], v[170:173], v[12:15]
	v_mfma_f32_16x16x32_bf16 v[4:7], v[182:185], v[170:173], v[4:7]
	v_mfma_f32_16x16x32_bf16 v[20:23], v[144:147], v[170:173], v[20:23]
	ds_read_b128 v[170:173], v186 offset:6144
	s_waitcnt lgkmcnt(3)
	v_mfma_f32_16x16x32_bf16 v[124:127], v[148:151], v[158:161], v[124:127]
	v_mfma_f32_16x16x32_bf16 v[96:99], v[152:155], v[158:161], v[96:99]
	v_mfma_f32_16x16x32_bf16 v[72:75], v[244:247], v[158:161], v[72:75]
	v_mfma_f32_16x16x32_bf16 v[48:51], v[248:251], v[158:161], v[48:51]
	ds_read_b128 v[158:161], v186 offset:16384
	s_waitcnt lgkmcnt(3)
	v_mfma_f32_16x16x32_bf16 v[120:123], v[148:151], v[162:165], v[120:123]
	v_mfma_f32_16x16x32_bf16 v[92:95], v[152:155], v[162:165], v[92:95]
	v_mfma_f32_16x16x32_bf16 v[68:71], v[244:247], v[162:165], v[68:71]
	v_mfma_f32_16x16x32_bf16 v[44:47], v[248:251], v[162:165], v[44:47]
	ds_read_b128 v[162:165], v186 offset:18432
	s_waitcnt lgkmcnt(3)
	v_mfma_f32_16x16x32_bf16 v[116:119], v[148:151], v[166:169], v[116:119]
	v_mfma_f32_16x16x32_bf16 v[88:91], v[152:155], v[166:169], v[88:91]
	v_mfma_f32_16x16x32_bf16 v[64:67], v[244:247], v[166:169], v[64:67]
	v_mfma_f32_16x16x32_bf16 v[40:43], v[248:251], v[166:169], v[40:43]
	ds_read_b128 v[166:169], v186 offset:20480
	s_waitcnt lgkmcnt(3)
	v_mfma_f32_16x16x32_bf16 v[112:115], v[148:151], v[170:173], v[112:115]
	v_mfma_f32_16x16x32_bf16 v[84:87], v[152:155], v[170:173], v[84:87]
	v_mfma_f32_16x16x32_bf16 v[60:63], v[244:247], v[170:173], v[60:63]
	v_mfma_f32_16x16x32_bf16 v[36:39], v[248:251], v[170:173], v[36:39]
	ds_read_b128 v[170:173], v186 offset:22528
	s_waitcnt lgkmcnt(3)
	v_mfma_f32_16x16x32_bf16 v[108:111], v[148:151], v[158:161], v[108:111]
	v_mfma_f32_16x16x32_bf16 v[80:83], v[152:155], v[158:161], v[80:83]
	v_mfma_f32_16x16x32_bf16 v[56:59], v[244:247], v[158:161], v[56:59]
	v_mfma_f32_16x16x32_bf16 v[32:35], v[248:251], v[158:161], v[32:35]
	s_add_u32 s62, s62, 0x80
	s_addc_u32 s63, s63, 0
	s_cmpk_eq_i32 s62, 0xf80
	s_waitcnt vmcnt(0) lgkmcnt(0)
	s_barrier
	s_cbranch_scc1 .Lgemm_496_exit
	s_xor_b32 s71, s70, 0x8000
	v_add3_u32 v143, v137, v142, s71
	v_add3_u32 v157, v139, v142, s71
	ds_read_b128 v[174:177], v143
	ds_read_b128 v[178:181], v143 offset:2048
	ds_read_b128 v[182:185], v143 offset:4096
	ds_read_b128 v[144:147], v143 offset:6144
	ds_read_b128 v[158:161], v157
	s_add_i32 s76, s66, s70
	s_add_i32 s77, s67, s70
	s_add_u32 s68, s62, s38
	s_addc_u32 s69, s63, s39
	s_add_i32 m0, s76, 0x0
	v_lshl_add_u64 v[242:243], v[128:129], 0, s[68:69]
	global_load_lds_dwordx4 v[242:243], off
	s_add_u32 s68, s62, s40
	s_addc_u32 s69, s63, s41
	s_add_i32 m0, s77, 0x0
	v_lshl_add_u64 v[242:243], v[130:131], 0, s[68:69]
	global_load_lds_dwordx4 v[242:243], off
	v_mfma_f32_16x16x32_bf16 v[28:31], v[148:151], v[162:165], v[28:31]
	v_mfma_f32_16x16x32_bf16 v[16:19], v[152:155], v[162:165], v[16:19]
	v_mfma_f32_16x16x32_bf16 v[8:11], v[244:247], v[162:165], v[8:11]
	v_mfma_f32_16x16x32_bf16 v[0:3], v[248:251], v[162:165], v[0:3]
	ds_read_b128 v[162:165], v157 offset:2048
	s_add_u32 s68, s62, s44
	s_addc_u32 s69, s63, s45
	s_add_i32 m0, s76, 0x2000
	v_lshl_add_u64 v[242:243], v[128:129], 0, s[68:69]
	global_load_lds_dwordx4 v[242:243], off
	s_add_u32 s68, s62, s48
	s_addc_u32 s69, s63, s49
	s_add_i32 m0, s77, 0x2000
	v_lshl_add_u64 v[242:243], v[130:131], 0, s[68:69]
	global_load_lds_dwordx4 v[242:243], off
	v_mfma_f32_16x16x32_bf16 v[104:107], v[148:151], v[166:169], v[104:107]
	v_mfma_f32_16x16x32_bf16 v[76:79], v[152:155], v[166:169], v[76:79]
	v_mfma_f32_16x16x32_bf16 v[52:55], v[244:247], v[166:169], v[52:55]
	v_mfma_f32_16x16x32_bf16 v[100:103], v[248:251], v[166:169], v[100:103]
	ds_read_b128 v[166:169], v157 offset:4096
	s_add_u32 s68, s62, s50
	s_addc_u32 s69, s63, s51
	s_add_i32 m0, s76, 0x4000
	v_lshl_add_u64 v[242:243], v[128:129], 0, s[68:69]
	global_load_lds_dwordx4 v[242:243], off
	s_add_u32 s68, s62, s54
	s_addc_u32 s69, s63, s55
	s_add_i32 m0, s77, 0x4000
	v_lshl_add_u64 v[242:243], v[130:131], 0, s[68:69]
	global_load_lds_dwordx4 v[242:243], off
	v_mfma_f32_16x16x32_bf16 v[24:27], v[148:151], v[170:173], v[24:27]
	v_mfma_f32_16x16x32_bf16 v[12:15], v[152:155], v[170:173], v[12:15]
	v_mfma_f32_16x16x32_bf16 v[4:7], v[244:247], v[170:173], v[4:7]
	v_mfma_f32_16x16x32_bf16 v[20:23], v[248:251], v[170:173], v[20:23]
	ds_read_b128 v[170:173], v157 offset:6144
	s_add_u32 s68, s62, s56
	s_addc_u32 s69, s63, s57
	s_add_i32 m0, s76, 0x6000
	v_lshl_add_u64 v[242:243], v[128:129], 0, s[68:69]
	global_load_lds_dwordx4 v[242:243], off
	s_add_u32 s68, s62, s58
	s_addc_u32 s69, s63, s59
	s_add_i32 m0, s77, 0x6000
	v_lshl_add_u64 v[242:243], v[130:131], 0, s[68:69]
	global_load_lds_dwordx4 v[242:243], off
	s_branch .LBB0_496
.Lgemm_496_exit:
	v_mfma_f32_16x16x32_bf16 v[28:31], v[148:151], v[162:165], v[28:31]
	v_mfma_f32_16x16x32_bf16 v[16:19], v[152:155], v[162:165], v[16:19]
	v_mfma_f32_16x16x32_bf16 v[8:11], v[244:247], v[162:165], v[8:11]
	v_mfma_f32_16x16x32_bf16 v[0:3], v[248:251], v[162:165], v[0:3]
	v_mfma_f32_16x16x32_bf16 v[104:107], v[148:151], v[166:169], v[104:107]
	v_mfma_f32_16x16x32_bf16 v[76:79], v[152:155], v[166:169], v[76:79]
	v_mfma_f32_16x16x32_bf16 v[52:55], v[244:247], v[166:169], v[52:55]
	v_mfma_f32_16x16x32_bf16 v[100:103], v[248:251], v[166:169], v[100:103]
	v_mfma_f32_16x16x32_bf16 v[24:27], v[148:151], v[170:173], v[24:27]
	v_mfma_f32_16x16x32_bf16 v[12:15], v[152:155], v[170:173], v[12:15]
	v_mfma_f32_16x16x32_bf16 v[4:7], v[244:247], v[170:173], v[4:7]
	v_mfma_f32_16x16x32_bf16 v[20:23], v[248:251], v[170:173], v[20:23]
	v_add_u32_e32 v157, v137, v142
	ds_read_b128 v[128:131], v157 offset:32768
	v_add_u32_e32 v190, v139, v142
	ds_read_b128 v[152:155], v190 offset:38912
	ds_read_b128 v[158:161], v190 offset:49152
	ds_read_b128 v[140:143], v190 offset:32768
	ds_read_b128 v[144:147], v190 offset:34816
	ds_read_b128 v[148:151], v190 offset:36864
	v_add_u32_e32 v139, v139, v138
	s_lshl_b32 s62, s65, 18
	s_waitcnt lgkmcnt(3)
	v_mfma_f32_16x16x32_bf16 v[162:165], v[128:131], v[158:161], v[108:111]
	s_nop 2
	ds_read_b128 v[108:111], v190 offset:53248
	s_waitcnt lgkmcnt(0)
	v_mfma_f32_16x16x32_bf16 v[166:169], v[128:131], v[108:111], v[104:107]
	s_nop 2
	ds_read_b128 v[104:107], v157 offset:34816
	v_mfma_f32_16x16x32_bf16 v[112:115], v[128:131], v[152:155], v[112:115]
	s_waitcnt lgkmcnt(0)
	v_mfma_f32_16x16x32_bf16 v[174:177], v[104:107], v[108:111], v[76:79]
	s_nop 2
	ds_read_b128 v[76:79], v157 offset:36864
	s_waitcnt lgkmcnt(0)
	v_mfma_f32_16x16x32_bf16 v[182:185], v[76:79], v[158:161], v[56:59]
	v_mfma_f32_16x16x32_bf16 v[186:189], v[76:79], v[108:111], v[52:55]
	s_nop 2
	ds_read_b128 v[52:55], v157 offset:38912
	ds_read_b128 v[56:59], v190 offset:55296
	v_mfma_f32_16x16x32_bf16 v[84:87], v[104:107], v[152:155], v[84:87]
	v_mfma_f32_16x16x32_bf16 v[178:181], v[76:79], v[152:155], v[60:63]
	s_nop 2
	v_cndmask_b32_e64 v60, 0, 1, s[60:61]
	s_waitcnt lgkmcnt(1)
	v_mfma_f32_16x16x32_bf16 v[152:155], v[52:55], v[152:155], v[36:39]
	v_readfirstlane_b32 s4, v60
	s_lshl_b32 s4, s4, 5
	s_add_i32 s60, s64, s4
	v_add_u32_e32 v36, v137, v138
	v_mfma_f32_16x16x32_bf16 v[124:127], v[128:131], v[140:143], v[124:127]
	s_ashr_i32 s61, s60, 31
	s_lshl_b64 s[60:61], s[60:61], 20
	s_or_b32 s60, s60, s62
	v_mfma_f32_16x16x32_bf16 v[116:119], v[128:131], v[148:151], v[116:119]
	v_mfma_f32_16x16x32_bf16 v[96:99], v[104:107], v[140:143], v[96:99]
	v_mfma_f32_16x16x32_bf16 v[88:91], v[104:107], v[148:151], v[88:91]
	v_mfma_f32_16x16x32_bf16 v[170:173], v[104:107], v[158:161], v[80:83]
	v_mfma_f32_16x16x32_bf16 v[72:75], v[76:79], v[140:143], v[72:75]
	v_mfma_f32_16x16x32_bf16 v[80:83], v[76:79], v[148:151], v[64:67]
	v_mfma_f32_16x16x32_bf16 v[140:143], v[52:55], v[140:143], v[48:51]
	s_nop 2
	ds_read_b128 v[48:51], v190 offset:51200
	v_mfma_f32_16x16x32_bf16 v[148:151], v[52:55], v[148:151], v[40:43]
	s_nop 2
	ds_read_b128 v[40:43], v139 offset:51200
	ds_read_b128 v[190:193], v139 offset:49152
	ds_read_b128 v[194:197], v139 offset:38912
	ds_read_b128 v[198:201], v139 offset:36864
	ds_read_b128 v[60:63], v36 offset:34816
	ds_read_b128 v[64:67], v36 offset:32768
	v_mfma_f32_16x16x32_bf16 v[120:123], v[128:131], v[144:147], v[120:123]
	v_mfma_f32_16x16x32_bf16 v[92:95], v[104:107], v[144:147], v[92:95]
	v_mfma_f32_16x16x32_bf16 v[68:71], v[76:79], v[144:147], v[68:71]
	v_mfma_f32_16x16x32_bf16 v[144:147], v[52:55], v[144:147], v[44:47]
	v_mfma_f32_16x16x32_bf16 v[158:161], v[52:55], v[158:161], v[32:35]
	ds_read_b128 v[202:205], v139 offset:34816
	ds_read_b128 v[206:209], v139 offset:32768
	s_nop 0
	ds_read_b128 v[32:35], v36 offset:38912
	ds_read_b128 v[44:47], v36 offset:36864
	ds_read_b128 v[210:213], v139 offset:53248
	ds_read_b128 v[36:39], v139 offset:55296
	s_waitcnt vmcnt(0)
	v_mfma_f32_16x16x32_bf16 v[100:103], v[52:55], v[108:111], v[100:103]
	v_lshl_or_b32 v110, v132, 2, v136
	v_mad_u32_u24 v108, v134, s15, 0
	v_lshlrev_b32_e32 v109, 2, v135
	s_waitcnt lgkmcnt(4)
	v_mfma_f32_16x16x32_bf16 v[124:127], v[64:67], v[206:209], v[124:127]
	v_mul_lo_u32 v110, v110, s22
	v_add3_u32 v110, v108, v109, v110
	v_add_u32_e32 v111, 0x400, v110
	v_mfma_f32_16x16x32_bf16 v[120:123], v[64:67], v[202:205], v[120:123]
	s_waitcnt lgkmcnt(0)
	s_barrier
	v_mfma_f32_16x16x32_bf16 v[116:119], v[64:67], v[198:201], v[116:119]
	v_mfma_f32_16x16x32_bf16 v[112:115], v[64:67], v[194:197], v[112:115]
	s_nop 3
	ds_write2_b32 v110, v124, v120 offset1:16
	ds_write2_b32 v110, v125, v121 offset0:136 offset1:152
	ds_write2_b32 v111, v126, v122 offset0:16 offset1:32
	v_mfma_f32_16x16x32_bf16 v[96:99], v[60:63], v[206:209], v[96:99]
	ds_write2_b32 v111, v127, v123 offset0:152 offset1:168
	ds_write2_b32 v110, v116, v112 offset0:32 offset1:48
	ds_write2_b32 v110, v117, v113 offset0:168 offset1:184
	ds_write2_b32 v111, v118, v114 offset0:48 offset1:64
	ds_write2_b32 v111, v119, v115 offset0:184 offset1:200
	v_add_u32_e32 v112, 0x2000, v110
	v_mfma_f32_16x16x32_bf16 v[92:95], v[60:63], v[202:205], v[92:95]
	v_add_u32_e32 v113, 0x2400, v110
	v_add_u32_e32 v114, 0x2800, v110
	v_add_u32_e32 v115, 0x4400, v110
	v_mfma_f32_16x16x32_bf16 v[88:91], v[60:63], v[198:201], v[88:91]
	v_add_u32_e32 v116, 0x4800, v110
	s_nop 2
	ds_write2_b32 v112, v96, v92 offset0:128 offset1:144
	ds_write2_b32 v113, v97, v93 offset0:8 offset1:24
	v_mfma_f32_16x16x32_bf16 v[84:87], v[60:63], v[194:197], v[84:87]
	ds_write2_b32 v113, v98, v94 offset0:144 offset1:160
	ds_write2_b32 v114, v99, v95 offset0:24 offset1:40
	s_nop 5
	ds_write2_b32 v112, v88, v84 offset0:160 offset1:176
	ds_write2_b32 v113, v89, v85 offset0:40 offset1:56
	ds_write2_b32 v113, v90, v86 offset0:176 offset1:192
	v_mfma_f32_16x16x32_bf16 v[72:75], v[44:47], v[206:209], v[72:75]
	ds_write2_b32 v114, v91, v87 offset0:56 offset1:72
	v_add_u32_e32 v117, 0x6400, v110
	v_add_u32_e32 v118, 0x6800, v110
	v_mfma_f32_16x16x32_bf16 v[68:71], v[44:47], v[202:205], v[68:71]
	v_add_u32_e32 v119, 0x6c00, v110
	v_mov_b32_e32 v123, v156
	v_mfma_f32_16x16x32_bf16 v[80:83], v[44:47], v[198:201], v[80:83]
	v_mfma_f32_16x16x32_bf16 v[84:87], v[44:47], v[194:197], v[178:181]
	s_nop 3
	ds_write2_b32 v115, v72, v68 offset1:16
	ds_write2_b32 v115, v73, v69 offset0:136 offset1:152
	ds_write2_b32 v116, v74, v70 offset0:16 offset1:32
	ds_write2_b32 v116, v75, v71 offset0:152 offset1:168
	ds_write2_b32 v115, v80, v84 offset0:32 offset1:48
	ds_write2_b32 v115, v81, v85 offset0:168 offset1:184
	v_mfma_f32_16x16x32_bf16 v[68:71], v[32:35], v[206:209], v[140:143]
	ds_write2_b32 v116, v82, v86 offset0:48 offset1:64
	ds_write2_b32 v116, v83, v87 offset0:184 offset1:200
	v_mfma_f32_16x16x32_bf16 v[72:75], v[32:35], v[202:205], v[144:147]
	v_mfma_f32_16x16x32_bf16 v[80:83], v[32:35], v[198:201], v[148:151]
	v_mfma_f32_16x16x32_bf16 v[92:95], v[64:67], v[190:193], v[162:165]
	s_nop 5
	ds_write2_b32 v117, v68, v72 offset0:128 offset1:144
	ds_write2_b32 v118, v69, v73 offset0:8 offset1:24
	ds_write2_b32 v118, v70, v74 offset0:144 offset1:160
	ds_write2_b32 v119, v71, v75 offset0:24 offset1:40
	v_mfma_f32_16x16x32_bf16 v[68:71], v[32:35], v[194:197], v[152:155]
	s_nop 7
	ds_write2_b32 v117, v80, v68 offset0:160 offset1:176
	ds_write2_b32 v118, v81, v69 offset0:40 offset1:56
	ds_write2_b32 v118, v82, v70 offset0:176 offset1:192
	ds_write2_b32 v119, v83, v71 offset0:56 offset1:72
	s_waitcnt lgkmcnt(0)
	s_barrier
	v_mfma_f32_16x16x32_bf16 v[80:83], v[64:67], v[210:213], v[166:169]
	v_ashrrev_i32_e32 v120, 5, v123
	v_ashrrev_i32_e32 v121, 31, v120
	v_lshlrev_b64 v[88:89], 10, v[120:121]
	v_lshlrev_b32_e32 v98, 4, v123
	v_lshl_add_u64 v[96:97], s[60:61], 0, v[88:89]
	v_and_b32_e32 v122, 0x1f0, v98
	v_or_b32_e32 v96, v96, v122
	v_mfma_f32_16x16x32_bf16 v[72:75], v[60:63], v[190:193], v[170:173]
	v_lshl_add_u64 v[108:109], s[72:73], 0, v[96:97]
	v_mad_u64_u32 v[120:121], s[62:63], v120, s22, v[122:123]
	v_mfma_f32_16x16x32_bf16 v[68:71], v[60:63], v[210:213], v[174:177]
	v_and_b32_e32 v121, 16, v123
	v_add3_u32 v120, v120, v121, 0
	s_mov_b64 s[62:63], 0
	v_mfma_f32_16x16x32_bf16 v[84:87], v[44:47], v[190:193], v[182:185]
	v_mfma_f32_16x16x32_bf16 v[88:91], v[44:47], v[210:213], v[186:189]
	v_mfma_f32_16x16x32_bf16 v[96:99], v[32:35], v[190:193], v[158:161]
	v_mfma_f32_16x16x32_bf16 v[100:103], v[32:35], v[210:213], v[100:103]

.LBB0_697:
	s_ashr_i32 s55, s54, 6
	v_mov_b32_e32 v10, v156
	s_and_b32 s2, s33, 63
	s_and_b32 s56, s54, 63
	s_lshl_b32 s50, s55, 8
	s_lshl_b32 s2, s2, 20
	v_ashrrev_i32_e32 v0, 3, v10
	s_ashr_i32 s51, s50, 31
	s_lshl_b32 s52, s56, 20
	v_xor_b32_e32 v6, v0, v10
	v_ashrrev_i32_e32 v1, 31, v0
	s_add_u32 s52, s10, s52
	v_lshlrev_b64 v[2:3], 12, v[0:1]
	v_lshlrev_b32_e32 v1, 4, v6
	s_addc_u32 s53, s11, 0
	s_lshl_b64 s[58:59], s[50:51], 12
	v_and_b32_e32 v128, 0x70, v1
	v_lshlrev_b32_e32 v1, 4, v10
	s_add_u32 s60, s12, s58
	v_add_u32_e32 v141, 0, v1
	s_addc_u32 s61, s13, s59
	v_lshl_add_u64 v[4:5], s[52:53], 0, v[2:3]
	v_add_u32_e32 v142, s8, v1
	v_readfirstlane_b32 s52, v141
	v_lshl_add_u64 v[4:5], v[4:5], 0, v[128:129]
	v_lshl_add_u64 v[6:7], s[60:61], 0, v[2:3]
	s_mov_b32 m0, s52
	v_readfirstlane_b32 s52, v142
	v_add_u32_e32 v1, 0x2000, v141
	v_lshl_add_u64 v[6:7], v[6:7], 0, v[128:129]
	s_barrier
	global_load_lds_dwordx4 v[4:5], off
	s_mov_b32 m0, s52
	v_readfirstlane_b32 s52, v1
	v_add_u32_e32 v1, 0x2000, v142
	global_load_lds_dwordx4 v[6:7], off
	v_lshl_add_u64 v[8:9], v[4:5], 0, s[4:5]
	s_mov_b32 m0, s52
	v_readfirstlane_b32 s52, v1
	v_add_u32_e32 v1, 0x4000, v141
	global_load_lds_dwordx4 v[8:9], off
	v_lshl_add_u64 v[8:9], v[6:7], 0, s[4:5]
	s_mov_b32 m0, s52
	v_readfirstlane_b32 s52, v1
	v_add_u32_e32 v1, 0x4000, v142
	global_load_lds_dwordx4 v[8:9], off
	v_lshl_add_u64 v[8:9], v[4:5], 0, s[16:17]
	s_mov_b32 m0, s52
	v_readfirstlane_b32 s52, v1
	v_add_u32_e32 v1, 0x6000, v141
	global_load_lds_dwordx4 v[8:9], off
	v_lshl_add_u64 v[8:9], v[6:7], 0, s[16:17]
	s_mov_b32 m0, s52
	v_readfirstlane_b32 s52, v1
	v_add_u32_e32 v1, 0x6000, v142
	global_load_lds_dwordx4 v[8:9], off
	v_lshl_add_u64 v[4:5], v[4:5], 0, s[18:19]
	s_mov_b32 m0, s52
	v_readfirstlane_b32 s52, v1
	global_load_lds_dwordx4 v[4:5], off
	v_lshl_add_u64 v[4:5], v[6:7], 0, s[18:19]
	s_mov_b32 m0, s52
	v_ashrrev_i32_e32 v1, 1, v10
	global_load_lds_dwordx4 v[4:5], off
	v_and_b32_e32 v136, 15, v10
	v_and_b32_e32 v137, 0xffffffc0, v1
	v_lshrrev_b32_e32 v11, 4, v10
	v_or_b32_e32 v1, v137, v136
	v_and_b32_e32 v6, 7, v10
	v_bfe_u32 v135, v10, 6, 1
	v_bfe_u32 v128, v10, 4, 2
	v_lshl_add_u32 v138, v1, 7, 0
	v_bitop3_b32 v1, v11, v6, 3 bitop3:0x6c
	v_lshlrev_b32_e32 v4, 13, v135
	v_lshlrev_b32_e32 v5, 7, v136
	v_lshlrev_b32_e32 v143, 4, v1
	v_bitop3_b32 v1, v128, v6, 4 bitop3:0x36
	v_bitop3_b32 v0, v0, 7, v10 bitop3:0x48
	s_waitcnt vmcnt(0)
	v_add3_u32 v140, s8, v4, v5
	v_lshlrev_b32_e32 v139, 4, v1
	v_lshl_add_u64 v[4:5], s[2:3], 0, v[2:3]
	v_lshlrev_b32_e32 v6, 4, v0
	v_lshl_add_u64 v[0:1], v[2:3], 0, s[58:59]
	v_or_b32_e32 v4, v4, v6
	v_or_b32_e32 v0, v0, v6
	v_lshl_add_u64 v[130:131], s[72:73], 0, v[4:5]
	v_lshl_add_u64 v[132:133], s[72:73], 0, v[0:1]
	s_mov_b64 s[52:53], 0
	s_mov_b32 s2, 0
	v_mov_b32_e32 v40, 0
	v_mov_b32_e32 v41, v129
	v_mov_b32_e32 v42, v129
	v_mov_b32_e32 v43, v129
	v_mov_b32_e32 v44, 0
	v_mov_b32_e32 v45, v129
	v_mov_b32_e32 v46, v129
	v_mov_b32_e32 v47, v129
	v_mov_b32_e32 v0, 0
	v_mov_b32_e32 v1, v129
	v_mov_b32_e32 v2, v129
	v_mov_b32_e32 v3, v129
	v_mov_b32_e32 v4, 0
	v_mov_b32_e32 v5, v129
	v_mov_b32_e32 v6, v129
	v_mov_b32_e32 v7, v129
	v_mov_b32_e32 v64, 0
	v_mov_b32_e32 v65, v129
	v_mov_b32_e32 v66, v129
	v_mov_b32_e32 v67, v129
	v_mov_b32_e32 v68, 0
	v_mov_b32_e32 v69, v129
	v_mov_b32_e32 v70, v129
	v_mov_b32_e32 v71, v129
	v_mov_b32_e32 v72, 0
	v_mov_b32_e32 v73, v129
	v_mov_b32_e32 v74, v129
	v_mov_b32_e32 v75, v129
	v_mov_b32_e32 v76, 0
	v_mov_b32_e32 v77, v129
	v_mov_b32_e32 v78, v129
	v_mov_b32_e32 v79, v129
	v_mov_b32_e32 v8, 0
	v_mov_b32_e32 v9, v129
	v_mov_b32_e32 v10, v129
	v_mov_b32_e32 v11, v129
	v_mov_b32_e32 v12, 0
	v_mov_b32_e32 v13, v129
	v_mov_b32_e32 v14, v129
	v_mov_b32_e32 v15, v129
	v_mov_b32_e32 v16, 0
	v_mov_b32_e32 v17, v129
	v_mov_b32_e32 v18, v129
	v_mov_b32_e32 v19, v129
	v_mov_b32_e32 v20, 0
	v_mov_b32_e32 v21, v129
	v_mov_b32_e32 v22, v129
	v_mov_b32_e32 v23, v129
	v_mov_b32_e32 v80, 0
	v_mov_b32_e32 v81, v129
	v_mov_b32_e32 v82, v129
	v_mov_b32_e32 v83, v129
	v_mov_b32_e32 v84, 0
	v_mov_b32_e32 v85, v129
	v_mov_b32_e32 v86, v129
	v_mov_b32_e32 v87, v129
	v_mov_b32_e32 v88, 0
	v_mov_b32_e32 v89, v129
	v_mov_b32_e32 v90, v129
	v_mov_b32_e32 v91, v129
	v_mov_b32_e32 v92, 0
	v_mov_b32_e32 v93, v129
	v_mov_b32_e32 v94, v129
	v_mov_b32_e32 v95, v129
	v_mov_b32_e32 v24, 0
	v_mov_b32_e32 v25, v129
	v_mov_b32_e32 v26, v129
	v_mov_b32_e32 v27, v129
	v_mov_b32_e32 v28, 0
	v_mov_b32_e32 v29, v129
	v_mov_b32_e32 v30, v129
	v_mov_b32_e32 v31, v129
	v_mov_b32_e32 v32, 0
	v_mov_b32_e32 v33, v129
	v_mov_b32_e32 v34, v129
	v_mov_b32_e32 v35, v129
	v_mov_b32_e32 v36, 0
	v_mov_b32_e32 v37, v129
	v_mov_b32_e32 v38, v129
	v_mov_b32_e32 v39, v129
	v_mov_b32_e32 v96, 0
	v_mov_b32_e32 v97, v129
	v_mov_b32_e32 v98, v129
	v_mov_b32_e32 v99, v129
	v_mov_b32_e32 v100, 0
	v_mov_b32_e32 v101, v129
	v_mov_b32_e32 v102, v129
	v_mov_b32_e32 v103, v129
	v_mov_b32_e32 v104, 0
	v_mov_b32_e32 v105, v129
	v_mov_b32_e32 v106, v129
	v_mov_b32_e32 v107, v129
	v_mov_b32_e32 v108, 0
	v_mov_b32_e32 v109, v129
	v_mov_b32_e32 v110, v129
	v_mov_b32_e32 v111, v129
	v_mov_b32_e32 v48, 0
	v_mov_b32_e32 v49, v129
	v_mov_b32_e32 v50, v129
	v_mov_b32_e32 v51, v129
	v_mov_b32_e32 v52, 0
	v_mov_b32_e32 v53, v129
	v_mov_b32_e32 v54, v129
	v_mov_b32_e32 v55, v129
	v_mov_b32_e32 v56, 0
	v_mov_b32_e32 v57, v129
	v_mov_b32_e32 v58, v129
	v_mov_b32_e32 v59, v129
	v_mov_b32_e32 v60, 0
	v_mov_b32_e32 v61, v129
	v_mov_b32_e32 v62, v129
	v_mov_b32_e32 v63, v129
	v_mov_b32_e32 v112, 0
	v_mov_b32_e32 v113, v129
	v_mov_b32_e32 v114, v129
	v_mov_b32_e32 v115, v129
	v_mov_b32_e32 v116, 0
	v_mov_b32_e32 v117, v129
	v_mov_b32_e32 v118, v129
	v_mov_b32_e32 v119, v129
	v_mov_b32_e32 v120, 0
	v_mov_b32_e32 v121, v129
	v_mov_b32_e32 v122, v129
	v_mov_b32_e32 v123, v129
	v_mov_b32_e32 v124, 0
	v_mov_b32_e32 v125, v129
	v_mov_b32_e32 v126, v129
	v_mov_b32_e32 v127, v129
	s_waitcnt vmcnt(0) lgkmcnt(0)
	s_barrier
	v_readfirstlane_b32 s57, v141
	v_readfirstlane_b32 s58, v142
	s_and_b32 s59, s2, 0x8000
	s_xor_b32 s62, s59, 0x8000
	v_add3_u32 v157, v138, v143, s59
	v_add3_u32 v186, v140, v143, s59
	ds_read_b128 v[174:177], v157
	ds_read_b128 v[178:181], v157 offset:2048
	ds_read_b128 v[182:185], v157 offset:4096
	ds_read_b128 v[144:147], v157 offset:6144
	ds_read_b128 v[158:161], v186
	ds_read_b128 v[162:165], v186 offset:2048
	ds_read_b128 v[166:169], v186 offset:4096
	ds_read_b128 v[170:173], v186 offset:6144
	s_add_i32 s63, s57, s62
	s_add_i32 s64, s58, s62
	s_add_u32 s60, s52, s24
	s_addc_u32 s61, s53, s25
	s_add_i32 m0, s63, 0x0
	v_lshl_add_u64 v[242:243], v[130:131], 0, s[60:61]
	global_load_lds_dwordx4 v[242:243], off
	s_add_u32 s60, s52, s26
	s_addc_u32 s61, s53, s27
	s_add_i32 m0, s64, 0x0
	v_lshl_add_u64 v[242:243], v[132:133], 0, s[60:61]
	global_load_lds_dwordx4 v[242:243], off
	s_add_u32 s60, s52, s36
	s_addc_u32 s61, s53, s37
	s_add_i32 m0, s63, 0x2000
	v_lshl_add_u64 v[242:243], v[130:131], 0, s[60:61]
	global_load_lds_dwordx4 v[242:243], off
	s_add_u32 s60, s52, s38
	s_addc_u32 s61, s53, s39
	s_add_i32 m0, s64, 0x2000
	v_lshl_add_u64 v[242:243], v[132:133], 0, s[60:61]
	global_load_lds_dwordx4 v[242:243], off
	s_add_u32 s60, s52, s40
	s_addc_u32 s61, s53, s41
	s_add_i32 m0, s63, 0x4000
	v_lshl_add_u64 v[242:243], v[130:131], 0, s[60:61]
	global_load_lds_dwordx4 v[242:243], off
	s_add_u32 s60, s52, s42
	s_addc_u32 s61, s53, s43
	s_add_i32 m0, s64, 0x4000
	v_lshl_add_u64 v[242:243], v[132:133], 0, s[60:61]
	global_load_lds_dwordx4 v[242:243], off
	s_add_u32 s60, s52, s44
	s_addc_u32 s61, s53, s45
	s_add_i32 m0, s63, 0x6000
	v_lshl_add_u64 v[242:243], v[130:131], 0, s[60:61]
	global_load_lds_dwordx4 v[242:243], off
	s_add_u32 s60, s52, s48
	s_addc_u32 s61, s53, s49
	s_add_i32 m0, s64, 0x6000
	v_lshl_add_u64 v[242:243], v[132:133], 0, s[60:61]
	global_load_lds_dwordx4 v[242:243], off
.LBB0_698:
	s_and_b32 s59, s2, 0x8000
	s_add_i32 s2, s2, 0x8000
	v_add3_u32 v157, v138, v139, s59
	v_add3_u32 v186, v140, v143, s59
	v_add3_u32 v187, v140, v139, s59
	s_waitcnt lgkmcnt(3)
	v_mfma_f32_16x16x32_bf16 v[124:127], v[174:177], v[158:161], v[124:127]
	v_mfma_f32_16x16x32_bf16 v[108:111], v[178:181], v[158:161], v[108:111]
	v_mfma_f32_16x16x32_bf16 v[92:95], v[182:185], v[158:161], v[92:95]
	v_mfma_f32_16x16x32_bf16 v[76:79], v[144:147], v[158:161], v[76:79]
	ds_read_b128 v[158:161], v186 offset:16384
	ds_read_b128 v[148:151], v157
	s_waitcnt lgkmcnt(4)
	v_mfma_f32_16x16x32_bf16 v[120:123], v[174:177], v[162:165], v[120:123]
	v_mfma_f32_16x16x32_bf16 v[104:107], v[178:181], v[162:165], v[104:107]
	v_mfma_f32_16x16x32_bf16 v[88:91], v[182:185], v[162:165], v[88:91]
	v_mfma_f32_16x16x32_bf16 v[72:75], v[144:147], v[162:165], v[72:75]
	ds_read_b128 v[162:165], v186 offset:18432
	ds_read_b128 v[152:155], v157 offset:2048
	s_waitcnt lgkmcnt(5)
	v_mfma_f32_16x16x32_bf16 v[116:119], v[174:177], v[166:169], v[116:119]
	v_mfma_f32_16x16x32_bf16 v[100:103], v[178:181], v[166:169], v[100:103]
	v_mfma_f32_16x16x32_bf16 v[84:87], v[182:185], v[166:169], v[84:87]
	v_mfma_f32_16x16x32_bf16 v[68:71], v[144:147], v[166:169], v[68:71]
	ds_read_b128 v[166:169], v186 offset:20480
	ds_read_b128 v[244:247], v157 offset:4096
	s_waitcnt lgkmcnt(6)
	v_mfma_f32_16x16x32_bf16 v[112:115], v[174:177], v[170:173], v[112:115]
	v_mfma_f32_16x16x32_bf16 v[96:99], v[178:181], v[170:173], v[96:99]
	v_mfma_f32_16x16x32_bf16 v[80:83], v[182:185], v[170:173], v[80:83]
	v_mfma_f32_16x16x32_bf16 v[64:67], v[144:147], v[170:173], v[64:67]
	ds_read_b128 v[170:173], v186 offset:22528
	ds_read_b128 v[248:251], v157 offset:6144
	s_waitcnt lgkmcnt(7)
	v_mfma_f32_16x16x32_bf16 v[60:63], v[174:177], v[158:161], v[60:63]
	v_mfma_f32_16x16x32_bf16 v[36:39], v[178:181], v[158:161], v[36:39]
	v_mfma_f32_16x16x32_bf16 v[20:23], v[182:185], v[158:161], v[20:23]
	v_mfma_f32_16x16x32_bf16 v[4:7], v[144:147], v[158:161], v[4:7]
	ds_read_b128 v[158:161], v187
	s_waitcnt lgkmcnt(6)
	v_mfma_f32_16x16x32_bf16 v[56:59], v[174:177], v[162:165], v[56:59]
	v_mfma_f32_16x16x32_bf16 v[32:35], v[178:181], v[162:165], v[32:35]
	v_mfma_f32_16x16x32_bf16 v[16:19], v[182:185], v[162:165], v[16:19]
	v_mfma_f32_16x16x32_bf16 v[0:3], v[144:147], v[162:165], v[0:3]
	ds_read_b128 v[162:165], v187 offset:2048
	s_waitcnt lgkmcnt(5)
	v_mfma_f32_16x16x32_bf16 v[52:55], v[174:177], v[166:169], v[52:55]
	v_mfma_f32_16x16x32_bf16 v[28:31], v[178:181], v[166:169], v[28:31]
	v_mfma_f32_16x16x32_bf16 v[12:15], v[182:185], v[166:169], v[12:15]
	v_mfma_f32_16x16x32_bf16 v[44:47], v[144:147], v[166:169], v[44:47]
	ds_read_b128 v[166:169], v187 offset:4096
	s_waitcnt lgkmcnt(4)
	v_mfma_f32_16x16x32_bf16 v[48:51], v[174:177], v[170:173], v[48:51]
	v_mfma_f32_16x16x32_bf16 v[24:27], v[178:181], v[170:173], v[24:27]
	v_mfma_f32_16x16x32_bf16 v[8:11], v[182:185], v[170:173], v[8:11]
	v_mfma_f32_16x16x32_bf16 v[40:43], v[144:147], v[170:173], v[40:43]
	ds_read_b128 v[170:173], v187 offset:6144
	s_waitcnt lgkmcnt(3)
	v_mfma_f32_16x16x32_bf16 v[124:127], v[148:151], v[158:161], v[124:127]
	v_mfma_f32_16x16x32_bf16 v[108:111], v[152:155], v[158:161], v[108:111]
	v_mfma_f32_16x16x32_bf16 v[92:95], v[244:247], v[158:161], v[92:95]
	v_mfma_f32_16x16x32_bf16 v[76:79], v[248:251], v[158:161], v[76:79]
	ds_read_b128 v[158:161], v187 offset:16384
	s_waitcnt lgkmcnt(3)
	v_mfma_f32_16x16x32_bf16 v[120:123], v[148:151], v[162:165], v[120:123]
	v_mfma_f32_16x16x32_bf16 v[104:107], v[152:155], v[162:165], v[104:107]
	v_mfma_f32_16x16x32_bf16 v[88:91], v[244:247], v[162:165], v[88:91]
	v_mfma_f32_16x16x32_bf16 v[72:75], v[248:251], v[162:165], v[72:75]
	ds_read_b128 v[162:165], v187 offset:18432
	s_waitcnt lgkmcnt(3)
	v_mfma_f32_16x16x32_bf16 v[116:119], v[148:151], v[166:169], v[116:119]
	v_mfma_f32_16x16x32_bf16 v[100:103], v[152:155], v[166:169], v[100:103]
	v_mfma_f32_16x16x32_bf16 v[84:87], v[244:247], v[166:169], v[84:87]
	v_mfma_f32_16x16x32_bf16 v[68:71], v[248:251], v[166:169], v[68:71]
	ds_read_b128 v[166:169], v187 offset:20480
	s_waitcnt lgkmcnt(3)
	v_mfma_f32_16x16x32_bf16 v[112:115], v[148:151], v[170:173], v[112:115]
	v_mfma_f32_16x16x32_bf16 v[96:99], v[152:155], v[170:173], v[96:99]
	v_mfma_f32_16x16x32_bf16 v[80:83], v[244:247], v[170:173], v[80:83]
	v_mfma_f32_16x16x32_bf16 v[64:67], v[248:251], v[170:173], v[64:67]
	ds_read_b128 v[170:173], v187 offset:22528
	s_waitcnt lgkmcnt(3)
	v_mfma_f32_16x16x32_bf16 v[60:63], v[148:151], v[158:161], v[60:63]
	v_mfma_f32_16x16x32_bf16 v[36:39], v[152:155], v[158:161], v[36:39]
	v_mfma_f32_16x16x32_bf16 v[20:23], v[244:247], v[158:161], v[20:23]
	v_mfma_f32_16x16x32_bf16 v[4:7], v[248:251], v[158:161], v[4:7]
	s_add_u32 s52, s52, 0x80
	s_addc_u32 s53, s53, 0
	s_cmpk_eq_i32 s52, 0xf80
	s_waitcnt vmcnt(0) lgkmcnt(0)
	s_barrier
	s_cbranch_scc1 .Lgemm_698_exit
	s_xor_b32 s62, s59, 0x8000
	v_add3_u32 v157, v138, v143, s62
	v_add3_u32 v186, v140, v143, s62
	ds_read_b128 v[174:177], v157
	ds_read_b128 v[178:181], v157 offset:2048
	ds_read_b128 v[182:185], v157 offset:4096
	ds_read_b128 v[144:147], v157 offset:6144
	ds_read_b128 v[158:161], v186
	s_add_i32 s63, s57, s59
	s_add_i32 s64, s58, s59
	s_add_u32 s60, s52, s24
	s_addc_u32 s61, s53, s25
	s_add_i32 m0, s63, 0x0
	v_lshl_add_u64 v[242:243], v[130:131], 0, s[60:61]
	global_load_lds_dwordx4 v[242:243], off
	s_add_u32 s60, s52, s26
	s_addc_u32 s61, s53, s27
	s_add_i32 m0, s64, 0x0
	v_lshl_add_u64 v[242:243], v[132:133], 0, s[60:61]
	global_load_lds_dwordx4 v[242:243], off
	v_mfma_f32_16x16x32_bf16 v[56:59], v[148:151], v[162:165], v[56:59]
	v_mfma_f32_16x16x32_bf16 v[32:35], v[152:155], v[162:165], v[32:35]
	v_mfma_f32_16x16x32_bf16 v[16:19], v[244:247], v[162:165], v[16:19]
	v_mfma_f32_16x16x32_bf16 v[0:3], v[248:251], v[162:165], v[0:3]
	ds_read_b128 v[162:165], v186 offset:2048
	s_add_u32 s60, s52, s36
	s_addc_u32 s61, s53, s37
	s_add_i32 m0, s63, 0x2000
	v_lshl_add_u64 v[242:243], v[130:131], 0, s[60:61]
	global_load_lds_dwordx4 v[242:243], off
	s_add_u32 s60, s52, s38
	s_addc_u32 s61, s53, s39
	s_add_i32 m0, s64, 0x2000
	v_lshl_add_u64 v[242:243], v[132:133], 0, s[60:61]
	global_load_lds_dwordx4 v[242:243], off
	v_mfma_f32_16x16x32_bf16 v[52:55], v[148:151], v[166:169], v[52:55]
	v_mfma_f32_16x16x32_bf16 v[28:31], v[152:155], v[166:169], v[28:31]
	v_mfma_f32_16x16x32_bf16 v[12:15], v[244:247], v[166:169], v[12:15]
	v_mfma_f32_16x16x32_bf16 v[44:47], v[248:251], v[166:169], v[44:47]
	ds_read_b128 v[166:169], v186 offset:4096
	s_add_u32 s60, s52, s40
	s_addc_u32 s61, s53, s41
	s_add_i32 m0, s63, 0x4000
	v_lshl_add_u64 v[242:243], v[130:131], 0, s[60:61]
	global_load_lds_dwordx4 v[242:243], off
	s_add_u32 s60, s52, s42
	s_addc_u32 s61, s53, s43
	s_add_i32 m0, s64, 0x4000
	v_lshl_add_u64 v[242:243], v[132:133], 0, s[60:61]
	global_load_lds_dwordx4 v[242:243], off
	v_mfma_f32_16x16x32_bf16 v[48:51], v[148:151], v[170:173], v[48:51]
	v_mfma_f32_16x16x32_bf16 v[24:27], v[152:155], v[170:173], v[24:27]
	v_mfma_f32_16x16x32_bf16 v[8:11], v[244:247], v[170:173], v[8:11]
	v_mfma_f32_16x16x32_bf16 v[40:43], v[248:251], v[170:173], v[40:43]
	ds_read_b128 v[170:173], v186 offset:6144
	s_add_u32 s60, s52, s44
	s_addc_u32 s61, s53, s45
	s_add_i32 m0, s63, 0x6000
	v_lshl_add_u64 v[242:243], v[130:131], 0, s[60:61]
	global_load_lds_dwordx4 v[242:243], off
	s_add_u32 s60, s52, s48
	s_addc_u32 s61, s53, s49
	s_add_i32 m0, s64, 0x6000
	v_lshl_add_u64 v[242:243], v[132:133], 0, s[60:61]
	global_load_lds_dwordx4 v[242:243], off
	s_branch .LBB0_698
.Lgemm_698_exit:
	v_mfma_f32_16x16x32_bf16 v[56:59], v[148:151], v[162:165], v[56:59]
	v_mfma_f32_16x16x32_bf16 v[32:35], v[152:155], v[162:165], v[32:35]
	v_mfma_f32_16x16x32_bf16 v[16:19], v[244:247], v[162:165], v[16:19]
	v_mfma_f32_16x16x32_bf16 v[0:3], v[248:251], v[162:165], v[0:3]
	v_mfma_f32_16x16x32_bf16 v[52:55], v[148:151], v[166:169], v[52:55]
	v_mfma_f32_16x16x32_bf16 v[28:31], v[152:155], v[166:169], v[28:31]
	v_mfma_f32_16x16x32_bf16 v[12:15], v[244:247], v[166:169], v[12:15]
	v_mfma_f32_16x16x32_bf16 v[44:47], v[248:251], v[166:169], v[44:47]
	v_mfma_f32_16x16x32_bf16 v[48:51], v[148:151], v[170:173], v[48:51]
	v_mfma_f32_16x16x32_bf16 v[24:27], v[152:155], v[170:173], v[24:27]
	v_mfma_f32_16x16x32_bf16 v[8:11], v[244:247], v[170:173], v[8:11]
	v_mfma_f32_16x16x32_bf16 v[40:43], v[248:251], v[170:173], v[40:43]
	v_add_u32_e32 v141, v138, v143
	ds_read_b128 v[170:173], v141 offset:36864
	ds_read_b128 v[186:189], v141 offset:38912
	ds_read_b128 v[130:133], v141 offset:32768
	ds_read_b128 v[162:165], v141 offset:34816
	v_add_u32_e32 v157, v140, v143
	ds_read_b128 v[142:145], v157 offset:32768
	ds_read_b128 v[146:149], v157 offset:34816
	ds_read_b128 v[150:153], v157 offset:36864
	ds_read_b128 v[158:161], v157 offset:38912
	s_waitcnt lgkmcnt(3)
	v_mfma_f32_16x16x32_bf16 v[174:177], v[170:173], v[142:145], v[92:95]
	s_lshl_b32 s2, s56, 8
	s_lshl_b32 s52, s56, 10
	s_nop 0
	v_add_u32_e32 v92, v140, v139
	v_add_u32_e32 v93, v138, v139
	v_mfma_f32_16x16x32_bf16 v[124:127], v[130:133], v[142:145], v[124:127]
	v_lshl_or_b32 v94, v128, 2, v137
	v_mul_lo_u32 v94, v94, s14
	s_and_b32 s52, s52, 0xe000
	s_waitcnt lgkmcnt(2)
	v_mfma_f32_16x16x32_bf16 v[120:123], v[130:133], v[146:149], v[120:123]
	s_add_u32 s52, s34, s52
	s_addc_u32 s53, s35, 0
	s_lshl_b64 s[50:51], s[50:51], 2
	v_mfma_f32_16x16x32_bf16 v[108:111], v[162:165], v[142:145], v[108:111]
	s_add_u32 s50, s52, s50
	s_addc_u32 s51, s53, s51
	v_mfma_f32_16x16x32_bf16 v[104:107], v[162:165], v[146:149], v[104:107]
	v_mfma_f32_16x16x32_bf16 v[178:181], v[170:173], v[146:149], v[88:91]
	s_waitcnt lgkmcnt(1)
	v_mfma_f32_16x16x32_bf16 v[182:185], v[170:173], v[150:153], v[84:87]
	s_waitcnt lgkmcnt(0)
	v_mfma_f32_16x16x32_bf16 v[190:193], v[170:173], v[158:161], v[80:83]
	s_nop 2
	ds_read_b128 v[80:83], v92 offset:51200
	ds_read_b128 v[84:87], v92 offset:49152
	ds_read_b128 v[194:197], v92 offset:38912
	ds_read_b128 v[198:201], v92 offset:36864
	ds_read_b128 v[202:205], v92 offset:34816
	ds_read_b128 v[206:209], v92 offset:32768
	v_mfma_f32_16x16x32_bf16 v[140:143], v[186:189], v[142:145], v[76:79]
	v_mfma_f32_16x16x32_bf16 v[144:147], v[186:189], v[146:149], v[72:75]
	s_nop 2
	ds_read_b128 v[72:75], v93 offset:38912
	ds_read_b128 v[76:79], v93 offset:36864
	ds_read_b128 v[88:91], v93 offset:34816
	ds_read_b128 v[210:213], v93 offset:32768
	v_lshlrev_b32_e32 v93, 2, v136
	v_mfma_f32_16x16x32_bf16 v[116:119], v[130:133], v[150:153], v[116:119]
	v_mfma_f32_16x16x32_bf16 v[112:115], v[130:133], v[158:161], v[112:115]
	v_mfma_f32_16x16x32_bf16 v[166:169], v[162:165], v[158:161], v[96:99]
	s_waitcnt lgkmcnt(0)
	v_mfma_f32_16x16x32_bf16 v[96:99], v[210:213], v[206:209], v[124:127]
	v_mfma_f32_16x16x32_bf16 v[120:123], v[210:213], v[202:205], v[120:123]
	v_mfma_f32_16x16x32_bf16 v[100:103], v[162:165], v[150:153], v[100:103]
	v_mfma_f32_16x16x32_bf16 v[148:151], v[186:189], v[150:153], v[68:71]
	ds_read_b128 v[152:155], v157 offset:55296
	ds_read_b128 v[214:217], v157 offset:53248
	ds_read_b128 v[218:221], v157 offset:51200
	ds_read_b128 v[222:225], v157 offset:49152
	v_mfma_f32_16x16x32_bf16 v[158:161], v[186:189], v[158:161], v[64:67]
	s_nop 2
	ds_read_b128 v[64:67], v92 offset:53248
	ds_read_b128 v[68:71], v92 offset:55296
	v_mad_u32_u24 v92, v135, s9, 0
	v_add3_u32 v94, v92, v93, v94
	v_mfma_f32_16x16x32_bf16 v[116:119], v[210:213], v[198:201], v[116:119]
	v_add_u32_e32 v95, 0x400, v94
	s_waitcnt vmcnt(0)
	s_waitcnt lgkmcnt(0)
	v_mfma_f32_16x16x32_bf16 v[112:115], v[210:213], v[194:197], v[112:115]
	s_barrier
	ds_write2_b32 v94, v96, v120 offset1:16
	v_mfma_f32_16x16x32_bf16 v[108:111], v[88:91], v[206:209], v[108:111]
	ds_write2_b32 v94, v97, v121 offset0:136 offset1:152
	ds_write2_b32 v95, v98, v122 offset0:16 offset1:32
	v_add_u32_e32 v96, 0x2000, v94
	v_mfma_f32_16x16x32_bf16 v[104:107], v[88:91], v[202:205], v[104:107]
	v_add_u32_e32 v97, 0x2400, v94
	v_add_u32_e32 v98, 0x2800, v94
	ds_write2_b32 v95, v99, v123 offset0:152 offset1:168
	ds_write2_b32 v94, v116, v112 offset0:32 offset1:48
	ds_write2_b32 v94, v117, v113 offset0:168 offset1:184
	ds_write2_b32 v95, v118, v114 offset0:48 offset1:64
	ds_write2_b32 v95, v119, v115 offset0:184 offset1:200
	v_mfma_f32_16x16x32_bf16 v[100:103], v[88:91], v[198:201], v[100:103]
	ds_write2_b32 v96, v108, v104 offset0:128 offset1:144
	ds_write2_b32 v97, v109, v105 offset0:8 offset1:24
	ds_write2_b32 v97, v110, v106 offset0:144 offset1:160
	v_mfma_f32_16x16x32_bf16 v[112:115], v[88:91], v[194:197], v[166:169]
	ds_write2_b32 v98, v111, v107 offset0:24 offset1:40
	v_add_u32_e32 v99, 0x4400, v94
	s_nop 5
	ds_write2_b32 v96, v100, v112 offset0:160 offset1:176
	ds_write2_b32 v97, v101, v113 offset0:40 offset1:56
	ds_write2_b32 v97, v102, v114 offset0:176 offset1:192
	v_mfma_f32_16x16x32_bf16 v[104:107], v[76:79], v[206:209], v[174:177]
	ds_write2_b32 v98, v103, v115 offset0:56 offset1:72
	v_add_u32_e32 v100, 0x4800, v94
	v_add_u32_e32 v101, 0x6400, v94
	v_mfma_f32_16x16x32_bf16 v[108:111], v[76:79], v[202:205], v[178:181]
	v_mfma_f32_16x16x32_bf16 v[112:115], v[76:79], v[198:201], v[182:185]
	v_mfma_f32_16x16x32_bf16 v[60:63], v[130:133], v[222:225], v[60:63]
	s_nop 5
	ds_write2_b32 v99, v104, v108 offset1:16
	ds_write2_b32 v99, v105, v109 offset0:136 offset1:152
	ds_write2_b32 v100, v106, v110 offset0:16 offset1:32
	v_mfma_f32_16x16x32_bf16 v[102:105], v[76:79], v[194:197], v[190:193]
	ds_write2_b32 v100, v107, v111 offset0:152 offset1:168
	s_nop 6
	ds_write2_b32 v99, v112, v102 offset0:32 offset1:48
	ds_write2_b32 v99, v113, v103 offset0:168 offset1:184
	v_mfma_f32_16x16x32_bf16 v[106:109], v[72:75], v[206:209], v[140:143]
	ds_write2_b32 v100, v114, v104 offset0:48 offset1:64
	ds_write2_b32 v100, v115, v105 offset0:184 offset1:200
	v_mfma_f32_16x16x32_bf16 v[102:105], v[72:75], v[202:205], v[144:147]
	v_mfma_f32_16x16x32_bf16 v[110:113], v[72:75], v[198:201], v[148:151]
	v_mfma_f32_16x16x32_bf16 v[56:59], v[130:133], v[218:221], v[56:59]
	s_nop 5
	ds_write2_b32 v101, v106, v102 offset0:128 offset1:144
	v_add_u32_e32 v102, 0x6800, v94
	ds_write2_b32 v102, v107, v103 offset0:8 offset1:24
	v_add_u32_e32 v103, 0x6c00, v94
	ds_write2_b32 v102, v108, v104 offset0:144 offset1:160
	ds_write2_b32 v103, v109, v105 offset0:24 offset1:40
	v_mfma_f32_16x16x32_bf16 v[104:107], v[72:75], v[194:197], v[158:161]
	s_nop 7
	ds_write2_b32 v101, v110, v104 offset0:160 offset1:176
	ds_write2_b32 v102, v111, v105 offset0:40 offset1:56
	ds_write2_b32 v102, v112, v106 offset0:176 offset1:192
	ds_write2_b32 v103, v113, v107 offset0:56 offset1:72
	v_mov_b32_e32 v106, v156
	s_waitcnt lgkmcnt(0)
	s_barrier
	v_mfma_f32_16x16x32_bf16 v[52:55], v[130:133], v[214:217], v[52:55]
	v_ashrrev_i32_e32 v107, 1, v106
	v_add_u32_e32 v92, s2, v107
	v_ashrrev_i32_e32 v93, 31, v92
	v_lshlrev_b64 v[104:105], 6, v[92:93]
	v_lshl_add_u64 v[104:105], s[0:1], 0, v[104:105]
	global_load_dwordx4 v[110:113], v[104:105], off
	global_load_dwordx4 v[114:117], v[104:105], off offset:16
	global_load_dwordx4 v[118:121], v[104:105], off offset:32
	global_load_dwordx4 v[122:125], v[104:105], off offset:48
	v_and_b32_e32 v104, 1, v106
	v_lshlrev_b32_e32 v108, 8, v104
	global_load_dwordx4 v[136:139], v108, s[50:51]
	global_load_dwordx4 v[140:143], v108, s[50:51] offset:16
	global_load_dwordx4 v[144:147], v108, s[50:51] offset:32
	global_load_dwordx4 v[148:151], v108, s[50:51] offset:48
	v_mul_lo_u32 v105, v107, s14
	v_mfma_f32_16x16x32_bf16 v[48:51], v[130:133], v[152:155], v[48:51]
	s_waitcnt vmcnt(7)
	v_add_f32_e32 v106, 0, v110
	v_add_f32_e32 v106, v111, v106
	v_add_f32_e32 v106, v112, v106
	v_add_f32_e32 v106, v113, v106
	s_waitcnt vmcnt(6)
	v_add_f32_e32 v106, v114, v106
	v_add_f32_e32 v106, v115, v106
	v_add_f32_e32 v106, v116, v106
	v_add_f32_e32 v106, v117, v106
	s_waitcnt vmcnt(5)
	v_add_f32_e32 v106, v118, v106
	v_add_f32_e32 v106, v119, v106
	v_add_f32_e32 v106, v120, v106
	v_mfma_f32_16x16x32_bf16 v[110:113], v[162:165], v[152:155], v[24:27]
	s_nop 2
	v_add_f32_e32 v24, v121, v106
	s_waitcnt vmcnt(4)
	v_add_f32_e32 v24, v122, v24
	v_add_f32_e32 v24, v123, v24
	v_mfma_f32_16x16x32_bf16 v[114:117], v[170:173], v[222:225], v[20:23]
	s_nop 2
	v_add_f32_e32 v20, v124, v24
	v_add_f32_e32 v20, v125, v20
	v_fmamk_f32 v20, v20, 0x3a000000, v134
	v_mfma_f32_16x16x32_bf16 v[118:121], v[170:173], v[218:221], v[16:19]
	v_cmp_gt_f32_e32 vcc, s15, v20
	s_nop 1
	v_mul_f32_e32 v16, 0x4b800000, v20
	v_cndmask_b32_e32 v16, v20, v16, vcc
	v_mfma_f32_16x16x32_bf16 v[122:125], v[170:173], v[214:217], v[12:15]
	s_nop 2
	v_rsq_f32_e32 v12, v16
	v_mul_u32_u24_e32 v13, 0x110, v104
	v_add3_u32 v107, 0, v105, v13
	v_mfma_f32_16x16x32_bf16 v[36:39], v[162:165], v[222:225], v[36:39]
	v_lshlrev_b32_e32 v105, 6, v104
	v_mfma_f32_16x16x32_bf16 v[32:35], v[162:165], v[218:221], v[32:35]
	v_mfma_f32_16x16x32_bf16 v[28:31], v[162:165], v[214:217], v[28:31]
	v_mfma_f32_16x16x32_bf16 v[130:133], v[170:173], v[152:155], v[8:11]
	s_nop 2
	v_mul_f32_e32 v8, 0x45800000, v12
	v_mfma_f32_16x16x32_bf16 v[158:161], v[186:189], v[222:225], v[4:7]
	s_nop 2
	ds_read_b128 v[4:7], v107
	ds_read_b128 v[14:17], v107 offset:16
	ds_read_b128 v[162:165], v107 offset:32
	ds_read_b128 v[166:169], v107 offset:48
	v_cndmask_b32_e32 v106, v12, v8, vcc
	s_waitcnt vmcnt(3) lgkmcnt(3)
	v_fmac_f32_e32 v139, v7, v106
	v_mfma_f32_16x16x32_bf16 v[170:173], v[186:189], v[218:221], v[0:3]
	s_waitcnt vmcnt(2) lgkmcnt(2)
	v_fmac_f32_e32 v143, v17, v106
	v_and_b32_e32 v20, 0xffffff80, v143
	s_waitcnt vmcnt(1) lgkmcnt(1)
	v_fma_f32 v24, v162, v106, v144
	v_fma_f32 v0, v4, v106, v136
	v_and_or_b32 v109, v0, s22, v105
	v_fma_f32 v0, v5, v106, v137
	v_mfma_f32_16x16x32_bf16 v[174:177], v[186:189], v[214:217], v[44:47]
	v_and_b32_e32 v0, 0xffffff80, v0
	v_or3_b32 v126, v105, v0, 1
	v_fma_f32 v0, v6, v106, v138
	v_fma_f32 v16, v16, v106, v142
	v_or3_b32 v137, v105, v20, 7
	v_mfma_f32_16x16x32_bf16 v[20:23], v[88:91], v[80:83], v[32:35]
	v_and_b32_e32 v24, 0xffffff80, v24
	v_and_b32_e32 v0, 0xffffff80, v0
	v_and_b32_e32 v4, 0xffffff80, v139
	v_fma_f32 v32, v163, v106, v145
	v_mfma_f32_16x16x32_bf16 v[152:155], v[186:189], v[152:155], v[40:43]
	v_fma_f32 v8, v14, v106, v140
	v_fma_f32 v12, v15, v106, v141
	v_and_b32_e32 v16, 0xffffff80, v16
	v_or3_b32 v138, v105, v24, 8
	v_mfma_f32_16x16x32_bf16 v[24:27], v[88:91], v[64:67], v[28:31]
	v_fmac_f32_e32 v147, v165, v106
	s_waitcnt vmcnt(0) lgkmcnt(0)
	v_fma_f32 v40, v166, v106, v148
	v_fma_f32 v44, v167, v106, v149
	v_and_b32_e32 v28, 0xffffff80, v32
	v_fma_f32 v32, v164, v106, v146
	v_or3_b32 v127, v105, v0, 2
	v_mfma_f32_16x16x32_bf16 v[0:3], v[210:213], v[84:87], v[60:63]
	v_and_b32_e32 v8, 0xffffff80, v8
	v_and_b32_e32 v12, 0xffffff80, v12
	v_or3_b32 v136, v105, v16, 6
	v_or3_b32 v60, v105, v4, 3
	v_mfma_f32_16x16x32_bf16 v[4:7], v[210:213], v[80:83], v[56:59]
	v_and_b32_e32 v32, 0xffffff80, v32
	v_and_b32_e32 v40, 0xffffff80, v40
	v_and_b32_e32 v44, 0xffffff80, v44
	v_mfma_f32_16x16x32_bf16 v[16:19], v[88:91], v[84:87], v[36:39]
	v_max_f32_e32 v56, v109, v109
	v_max_f32_e32 v57, v126, v126
	v_or3_b32 v128, v105, v8, 4
	v_and_b32_e32 v36, 0xffffff80, v147
	v_mfma_f32_16x16x32_bf16 v[8:11], v[210:213], v[64:67], v[52:55]
	v_or3_b32 v135, v105, v12, 5
	v_or3_b32 v139, v105, v28, 9
	v_fmac_f32_e32 v151, v169, v106
	v_mfma_f32_16x16x32_bf16 v[28:31], v[88:91], v[68:71], v[110:113]
	v_or3_b32 v88, v105, v32, 10
	v_or3_b32 v89, v105, v36, 11
	v_or3_b32 v90, v105, v40, 12
	v_mfma_f32_16x16x32_bf16 v[32:35], v[76:79], v[84:87], v[114:117]
	v_or3_b32 v91, v105, v44, 13
	v_and_b32_e32 v52, 0xffffff80, v151
	v_cmp_eq_u32_e32 vcc, 1, v104
	v_mfma_f32_16x16x32_bf16 v[36:39], v[76:79], v[80:83], v[118:121]
	v_mfma_f32_16x16x32_bf16 v[40:43], v[76:79], v[64:67], v[122:125]
	v_mfma_f32_16x16x32_bf16 v[44:47], v[76:79], v[68:71], v[130:133]
	v_max_f32_e32 v78, v56, v57
	v_min_f32_e32 v79, v56, v57
	v_or3_b32 v77, v105, v52, 15
	v_mfma_f32_16x16x32_bf16 v[56:59], v[72:75], v[64:67], v[174:177]
	v_max_f32_e32 v64, v127, v127
	v_max_f32_e32 v65, v60, v60
	v_max_f32_e32 v66, v65, v64
	v_min_f32_e32 v64, v65, v64
	v_max_f32_e32 v65, v135, v135
	v_max_f32_e32 v67, v128, v128
	v_mfma_f32_16x16x32_bf16 v[12:15], v[210:213], v[68:71], v[48:51]
	s_nop 2
	v_fma_f32 v48, v168, v106, v150
	v_mfma_f32_16x16x32_bf16 v[60:63], v[72:75], v[68:71], v[152:155]
	v_max_f32_e32 v68, v67, v65
	v_min_f32_e32 v65, v67, v65
	v_max_f32_e32 v67, v136, v136
	v_max_f32_e32 v69, v137, v137
	v_and_b32_e32 v48, 0xffffff80, v48
	v_max_f32_e32 v70, v69, v67
	v_min_f32_e32 v67, v69, v67
	v_max_f32_e32 v69, v139, v139
	v_max_f32_e32 v71, v138, v138
	v_or3_b32 v76, v105, v48, 14
	v_mfma_f32_16x16x32_bf16 v[48:51], v[72:75], v[84:87], v[158:161]
	v_mfma_f32_16x16x32_bf16 v[52:55], v[72:75], v[80:83], v[170:173]
	v_max_f32_e32 v72, v71, v69
	v_min_f32_e32 v69, v71, v69
	v_max_f32_e32 v71, v88, v88
	v_max_f32_e32 v73, v89, v89
	v_max_f32_e32 v74, v73, v71
	v_min_f32_e32 v71, v73, v71
	v_max_f32_e32 v73, v91, v91
	v_max_f32_e32 v75, v90, v90
	v_max_f32_e32 v80, v75, v73
	v_min_f32_e32 v73, v75, v73
	v_max_f32_e32 v75, v76, v76
	v_max_f32_e32 v76, v77, v77
	v_max_f32_e32 v77, v76, v75
	v_min_f32_e32 v75, v76, v75
	v_max_f32_e32 v76, v78, v64
	v_min_f32_e32 v64, v78, v64
	v_max_f32_e32 v78, v79, v66
	v_min_f32_e32 v66, v79, v66
	v_max_f32_e32 v79, v67, v68
	v_min_f32_e32 v67, v67, v68
	v_max_f32_e32 v68, v70, v65
	v_min_f32_e32 v65, v70, v65
	v_max_f32_e32 v70, v72, v71
	v_min_f32_e32 v71, v72, v71
	v_max_f32_e32 v72, v69, v74
	v_min_f32_e32 v69, v69, v74
	v_max_f32_e32 v74, v75, v80
	v_min_f32_e32 v75, v75, v80
	v_max_f32_e32 v80, v77, v73
	v_min_f32_e32 v73, v77, v73
	v_max_f32_e32 v77, v76, v78
	v_min_f32_e32 v76, v76, v78
	v_max_f32_e32 v78, v64, v66
	v_min_f32_e32 v64, v64, v66
	v_max_f32_e32 v66, v65, v67
	v_min_f32_e32 v65, v65, v67
	v_max_f32_e32 v67, v68, v79
	v_min_f32_e32 v68, v68, v79
	v_max_f32_e32 v79, v70, v72
	v_min_f32_e32 v70, v70, v72
	v_max_f32_e32 v72, v71, v69
	v_min_f32_e32 v69, v71, v69
	v_max_f32_e32 v71, v73, v75
	v_min_f32_e32 v73, v73, v75
	v_max_f32_e32 v75, v80, v74
	v_min_f32_e32 v74, v80, v74
	v_max_f32_e32 v80, v77, v65
	v_min_f32_e32 v65, v77, v65
	v_max_f32_e32 v77, v76, v66
	v_min_f32_e32 v66, v76, v66
	v_max_f32_e32 v76, v78, v68
	v_min_f32_e32 v68, v78, v68
	v_max_f32_e32 v78, v64, v67
	v_min_f32_e32 v64, v64, v67
	v_max_f32_e32 v67, v73, v79
	v_min_f32_e32 v73, v73, v79
	v_max_f32_e32 v79, v71, v70
	v_min_f32_e32 v70, v71, v70
	v_max_f32_e32 v71, v74, v72
	v_min_f32_e32 v72, v74, v72
	v_max_f32_e32 v74, v75, v69
	v_min_f32_e32 v69, v75, v69
	v_max_f32_e32 v75, v80, v76
	v_min_f32_e32 v76, v80, v76
	v_max_f32_e32 v80, v77, v78
	v_min_f32_e32 v77, v77, v78
	v_max_f32_e32 v78, v65, v68
	v_min_f32_e32 v81, v65, v68
	v_max_f32_e32 v82, v66, v64
	v_min_f32_e32 v83, v66, v64
	v_max_f32_e32 v84, v72, v73
	v_min_f32_e32 v72, v72, v73
	v_max_f32_e32 v73, v69, v70
	v_min_f32_e32 v85, v69, v70
	v_max_f32_e32 v86, v71, v67
	v_min_f32_e32 v87, v71, v67
	global_load_dwordx4 v[64:67], v108, s[50:51] offset:80
	global_load_dwordx4 v[68:71], v108, s[50:51] offset:64
	v_max_f32_e32 v88, v74, v79
	v_min_f32_e32 v74, v74, v79
	v_max_f32_e32 v79, v75, v80
	v_min_f32_e32 v75, v75, v80
	v_max_f32_e32 v80, v76, v77
	v_min_f32_e32 v89, v76, v77
	v_max_f32_e32 v76, v85, v72
	v_min_f32_e32 v72, v85, v72
	v_max_f32_e32 v90, v78, v82
	v_min_f32_e32 v82, v78, v82
	v_max_f32_e32 v91, v81, v83
	v_min_f32_e32 v81, v81, v83
	v_max_f32_e32 v83, v73, v84
	v_min_f32_e32 v84, v73, v84
	v_max_f32_e32 v85, v74, v87
	v_min_f32_e32 v87, v74, v87
	v_max_f32_e32 v109, v88, v86
	v_min_f32_e32 v86, v88, v86
	v_max_f32_e32 v88, v79, v72
	v_min_f32_e32 v110, v79, v72
	v_max_f32_e32 v111, v75, v76
	v_min_f32_e32 v112, v75, v76
	global_load_dwordx4 v[72:75], v108, s[50:51] offset:112
	global_load_dwordx4 v[76:79], v108, s[50:51] offset:96
	v_max_f32_e32 v113, v80, v84
	v_min_f32_e32 v80, v80, v84
	v_max_f32_e32 v84, v89, v83
	v_min_f32_e32 v83, v89, v83
	v_max_f32_e32 v89, v90, v87
	v_min_f32_e32 v87, v90, v87
	v_max_f32_e32 v90, v82, v85
	v_min_f32_e32 v82, v82, v85
	v_max_f32_e32 v85, v91, v86
	v_min_f32_e32 v86, v91, v86
	v_max_f32_e32 v91, v81, v109
	v_min_f32_e32 v81, v81, v109
	v_max_f32_e32 v109, v88, v89
	v_min_f32_e32 v88, v88, v89
	v_max_f32_e32 v89, v111, v90
	v_min_f32_e32 v90, v111, v90
	v_max_f32_e32 v111, v113, v85
	v_min_f32_e32 v85, v113, v85
	v_max_f32_e32 v113, v84, v91
	v_min_f32_e32 v84, v84, v91
	v_max_f32_e32 v91, v110, v87
	v_min_f32_e32 v87, v110, v87
	v_max_f32_e32 v110, v112, v82
	v_min_f32_e32 v82, v112, v82
	v_max_f32_e32 v112, v80, v86
	v_min_f32_e32 v80, v80, v86
	v_max_f32_e32 v86, v83, v81
	v_min_f32_e32 v81, v83, v81
	v_max_f32_e32 v115, v88, v85
	v_min_f32_e32 v116, v88, v85
	v_max_f32_e32 v117, v90, v84
	v_min_f32_e32 v118, v90, v84
	v_max_f32_e32 v120, v110, v86
	v_min_f32_e32 v110, v110, v86
	v_max_f32_e32 v121, v87, v80
	v_min_f32_e32 v122, v87, v80
	v_max_f32_e32 v123, v82, v81
	v_min_f32_e32 v124, v82, v81
	ds_read_b128 v[80:83], v107 offset:80
	ds_read_b128 v[84:87], v107 offset:64
	v_max_f32_e32 v114, v109, v111
	v_min_f32_e32 v109, v109, v111
	v_max_f32_e32 v111, v89, v113
	v_min_f32_e32 v113, v89, v113
	v_max_f32_e32 v119, v91, v112
	v_min_f32_e32 v112, v91, v112
	ds_read_b128 v[88:91], v107 offset:96
	v_min_f32_e32 v125, v114, v111
	v_min_f32_e32 v127, v115, v117
	v_min_f32_e32 v130, v119, v120
	v_min_f32_e32 v126, v109, v113
	v_min_f32_e32 v128, v116, v118
	v_min_f32_e32 v131, v112, v110
	v_min_f32_e32 v132, v121, v123
	v_min_f32_e32 v133, v122, v124
	s_waitcnt vmcnt(3) lgkmcnt(2)
	v_fma_f32 v64, v80, v106, v64
	v_and_b32_e32 v64, 0xffffff80, v64
	v_or3_b32 v80, v105, v64, 20
	v_fma_f32 v64, v81, v106, v65
	v_and_b32_e32 v64, 0xffffff80, v64
	v_or3_b32 v81, v105, v64, 21
	v_fma_f32 v64, v82, v106, v66
	v_and_b32_e32 v64, 0xffffff80, v64
	v_fmac_f32_e32 v67, v83, v106
	v_or3_b32 v82, v105, v64, 22
	v_and_b32_e32 v64, 0xffffff80, v67
	v_or3_b32 v83, v105, v64, 23
	ds_read_b128 v[64:67], v107 offset:112
	s_waitcnt vmcnt(2) lgkmcnt(2)
	v_fma_f32 v68, v84, v106, v68
	v_fma_f32 v69, v85, v106, v69
	v_and_b32_e32 v68, 0xffffff80, v68
	v_and_b32_e32 v69, 0xffffff80, v69
	v_fma_f32 v70, v86, v106, v70
	v_fmac_f32_e32 v71, v87, v106
	v_or3_b32 v68, v105, v68, 16
	v_or3_b32 v69, v105, v69, 17
	v_and_b32_e32 v70, 0xffffff80, v70
	v_and_b32_e32 v71, 0xffffff80, v71
	v_or3_b32 v70, v105, v70, 18
	v_or3_b32 v71, v105, v71, 19
	v_max_f32_e32 v69, v69, v69
	v_max_f32_e32 v68, v68, v68
	s_waitcnt vmcnt(0) lgkmcnt(1)
	v_fma_f32 v76, v88, v106, v76
	v_fma_f32 v77, v89, v106, v77
	s_waitcnt lgkmcnt(0)
	v_fma_f32 v64, v64, v106, v72
	v_max_f32_e32 v72, v68, v69
	v_min_f32_e32 v68, v68, v69
	v_max_f32_e32 v69, v70, v70
	v_max_f32_e32 v70, v71, v71
	v_and_b32_e32 v76, 0xffffff80, v76
	v_and_b32_e32 v77, 0xffffff80, v77
	v_fma_f32 v78, v90, v106, v78
	v_fmac_f32_e32 v79, v91, v106
	v_fma_f32 v65, v65, v106, v73
	v_fmac_f32_e32 v75, v67, v106
	v_max_f32_e32 v71, v70, v69
	v_min_f32_e32 v69, v70, v69
	v_max_f32_e32 v70, v81, v81
	v_max_f32_e32 v73, v80, v80
	v_or3_b32 v76, v105, v76, 24
	v_or3_b32 v77, v105, v77, 25
	v_and_b32_e32 v78, 0xffffff80, v78
	v_and_b32_e32 v79, 0xffffff80, v79
	v_and_b32_e32 v64, 0xffffff80, v64
	v_and_b32_e32 v65, 0xffffff80, v65
	v_fma_f32 v66, v66, v106, v74
	v_and_b32_e32 v67, 0xffffff80, v75
	v_max_f32_e32 v74, v73, v70
	v_min_f32_e32 v70, v73, v70
	v_max_f32_e32 v73, v82, v82
	v_max_f32_e32 v75, v83, v83
	v_or3_b32 v78, v105, v78, 26
	v_or3_b32 v79, v105, v79, 27
	v_or3_b32 v64, v105, v64, 28
	v_or3_b32 v65, v105, v65, 29
	v_and_b32_e32 v66, 0xffffff80, v66
	v_max_f32_e32 v80, v75, v73
	v_min_f32_e32 v73, v75, v73
	v_max_f32_e32 v75, v77, v77
	v_max_f32_e32 v76, v76, v76
	v_or3_b32 v66, v105, v66, 30
	v_or3_b32 v67, v105, v67, 31
	v_max_f32_e32 v77, v76, v75
	v_min_f32_e32 v75, v76, v75
	v_max_f32_e32 v76, v78, v78
	v_max_f32_e32 v78, v79, v79
	v_max_f32_e32 v65, v65, v65
	v_max_f32_e32 v64, v64, v64
	v_max_f32_e32 v79, v78, v76
	v_min_f32_e32 v76, v78, v76
	v_max_f32_e32 v78, v64, v65
	v_min_f32_e32 v64, v64, v65
	v_max_f32_e32 v65, v66, v66
	v_max_f32_e32 v66, v67, v67
	v_max_f32_e32 v67, v66, v65
	v_min_f32_e32 v65, v66, v65
	v_max_f32_e32 v66, v72, v69
	v_min_f32_e32 v69, v72, v69
	v_max_f32_e32 v72, v68, v71
	v_min_f32_e32 v68, v68, v71
	v_max_f32_e32 v71, v73, v74
	v_min_f32_e32 v73, v73, v74
	v_max_f32_e32 v74, v80, v70
	v_min_f32_e32 v70, v80, v70
	v_max_f32_e32 v80, v77, v76
	v_min_f32_e32 v76, v77, v76
	v_max_f32_e32 v77, v75, v79
	v_min_f32_e32 v75, v75, v79
	v_max_f32_e32 v79, v65, v78
	v_min_f32_e32 v65, v65, v78
	v_max_f32_e32 v78, v67, v64
	v_min_f32_e32 v64, v67, v64
	v_max_f32_e32 v67, v66, v72
	v_min_f32_e32 v66, v66, v72
	v_max_f32_e32 v72, v69, v68
	v_min_f32_e32 v68, v69, v68
	v_max_f32_e32 v69, v70, v73
	v_min_f32_e32 v70, v70, v73
	v_max_f32_e32 v73, v74, v71
	v_min_f32_e32 v71, v74, v71
	v_max_f32_e32 v74, v80, v77
	v_min_f32_e32 v77, v80, v77
	v_max_f32_e32 v80, v76, v75
	v_min_f32_e32 v75, v76, v75
	v_max_f32_e32 v76, v64, v65
	v_min_f32_e32 v64, v64, v65
	v_max_f32_e32 v65, v78, v79
	v_min_f32_e32 v78, v78, v79
	v_max_f32_e32 v79, v67, v70
	v_min_f32_e32 v67, v67, v70
	v_max_f32_e32 v70, v66, v69
	v_min_f32_e32 v66, v66, v69
	v_max_f32_e32 v69, v72, v71
	v_min_f32_e32 v71, v72, v71
	v_max_f32_e32 v72, v68, v73
	v_min_f32_e32 v68, v68, v73
	v_max_f32_e32 v73, v64, v74
	v_min_f32_e32 v64, v64, v74
	v_max_f32_e32 v74, v76, v77
	v_min_f32_e32 v76, v76, v77
	v_max_f32_e32 v77, v78, v80
	v_min_f32_e32 v78, v78, v80
	v_max_f32_e32 v80, v65, v75
	v_min_f32_e32 v65, v65, v75
	v_max_f32_e32 v75, v79, v69
	v_min_f32_e32 v69, v79, v69
	v_max_f32_e32 v79, v70, v72
	v_min_f32_e32 v70, v70, v72
	v_max_f32_e32 v72, v67, v71
	v_min_f32_e32 v67, v67, v71
	v_max_f32_e32 v71, v66, v68
	v_min_f32_e32 v66, v66, v68
	v_max_f32_e32 v68, v78, v64
	v_min_f32_e32 v64, v78, v64
	v_max_f32_e32 v78, v65, v76
	v_min_f32_e32 v65, v65, v76
	v_max_f32_e32 v76, v77, v73
	v_min_f32_e32 v73, v77, v73
	v_max_f32_e32 v77, v80, v74
	v_min_f32_e32 v74, v80, v74
	v_max_f32_e32 v80, v75, v79
	v_min_f32_e32 v75, v75, v79
	v_max_f32_e32 v79, v69, v70
	v_min_f32_e32 v69, v69, v70
	v_max_f32_e32 v70, v72, v71
	v_min_f32_e32 v71, v72, v71
	v_max_f32_e32 v72, v67, v66
	v_min_f32_e32 v66, v67, v66
	v_max_f32_e32 v67, v65, v64
	v_min_f32_e32 v64, v65, v64
	v_max_f32_e32 v65, v78, v68
	v_min_f32_e32 v68, v78, v68
	v_max_f32_e32 v78, v74, v73
	v_min_f32_e32 v73, v74, v73
	v_max_f32_e32 v74, v77, v76
	v_min_f32_e32 v76, v77, v76
	v_max_f32_e32 v77, v80, v64
	v_min_f32_e32 v64, v80, v64
	v_max_f32_e32 v80, v75, v67
	v_min_f32_e32 v67, v75, v67
	v_max_f32_e32 v75, v79, v68
	v_min_f32_e32 v68, v79, v68
	v_max_f32_e32 v79, v69, v65
	v_min_f32_e32 v65, v69, v65
	v_max_f32_e32 v69, v70, v73
	v_min_f32_e32 v70, v70, v73
	v_max_f32_e32 v73, v71, v78
	v_min_f32_e32 v71, v71, v78
	v_max_f32_e32 v78, v72, v76
	v_min_f32_e32 v72, v72, v76
	v_max_f32_e32 v76, v66, v74
	v_min_f32_e32 v66, v66, v74
	v_max_f32_e32 v74, v77, v69
	v_min_f32_e32 v69, v77, v69
	v_max_f32_e32 v77, v80, v73
	v_min_f32_e32 v73, v80, v73
	v_max_f32_e32 v80, v75, v78
	v_min_f32_e32 v75, v75, v78
	v_max_f32_e32 v78, v79, v76
	v_min_f32_e32 v76, v79, v76
	v_max_f32_e32 v79, v64, v70
	v_min_f32_e32 v64, v64, v70
	v_max_f32_e32 v70, v67, v71
	v_min_f32_e32 v67, v67, v71
	v_max_f32_e32 v71, v68, v72
	v_min_f32_e32 v68, v68, v72
	v_max_f32_e32 v72, v65, v66
	v_min_f32_e32 v65, v65, v66
	v_max_f32_e32 v81, v74, v80
	v_min_f32_e32 v74, v74, v80
	v_max_f32_e32 v80, v77, v78
	v_min_f32_e32 v77, v77, v78
	v_max_f32_e32 v78, v69, v75
	v_min_f32_e32 v75, v69, v75
	v_max_f32_e32 v82, v73, v76
	v_min_f32_e32 v73, v73, v76
	v_max_f32_e32 v76, v79, v71
	v_min_f32_e32 v79, v79, v71
	v_max_f32_e32 v83, v70, v72
	v_min_f32_e32 v72, v70, v72
	v_max_f32_e32 v84, v64, v68
	v_min_f32_e32 v85, v64, v68
	v_max_f32_e32 v86, v67, v65
	v_min_f32_e32 v87, v67, v65
	global_load_dwordx4 v[64:67], v108, s[50:51] offset:144
	global_load_dwordx4 v[68:71], v108, s[50:51] offset:128
	v_min_f32_e32 v91, v75, v73
	v_min_f32_e32 v137, v84, v86
	v_min_f32_e32 v138, v85, v87
	v_min_f32_e32 v90, v78, v82
	v_min_f32_e32 v136, v79, v72
	v_max3_f32 v111, v114, v111, v138
	v_max3_f32 v85, v125, v85, v87
	v_max3_f32 v87, v109, v113, v137
	v_max3_f32 v109, v127, v79, v72
	v_max3_f32 v72, v119, v120, v91
	v_max3_f32 v73, v130, v75, v73
	v_min_f32_e32 v88, v81, v80
	v_min_f32_e32 v89, v74, v77
	v_min_f32_e32 v135, v76, v83
	v_max3_f32 v83, v128, v76, v83
	v_max3_f32 v90, v112, v110, v90
	v_max3_f32 v82, v131, v78, v82
	v_max3_f32 v91, v132, v74, v77
	v_max3_f32 v80, v133, v81, v80
	v_max_f32_e32 v81, v111, v72
	v_min_f32_e32 v110, v111, v72
	v_max_f32_e32 v111, v85, v73
	v_min_f32_e32 v85, v85, v73
	global_load_dwordx4 v[72:75], v108, s[50:51] offset:176
	global_load_dwordx4 v[76:79], v108, s[50:51] offset:160
	v_max3_f32 v84, v126, v84, v86
	v_max3_f32 v86, v115, v117, v136
	v_max3_f32 v113, v116, v118, v135
	v_max3_f32 v89, v121, v123, v89
	v_max3_f32 v88, v122, v124, v88
	v_max_f32_e32 v112, v87, v90
	v_min_f32_e32 v87, v87, v90
	v_max_f32_e32 v90, v84, v82
	v_min_f32_e32 v82, v84, v82
	v_max_f32_e32 v84, v86, v89
	v_min_f32_e32 v86, v86, v89
	v_max_f32_e32 v89, v109, v91
	v_min_f32_e32 v91, v109, v91
	v_max_f32_e32 v109, v113, v88
	v_min_f32_e32 v88, v113, v88
	v_max_f32_e32 v113, v83, v80
	v_min_f32_e32 v80, v83, v80
	v_max_f32_e32 v83, v81, v84
	v_min_f32_e32 v81, v81, v84
	v_max_f32_e32 v84, v111, v89
	v_min_f32_e32 v89, v111, v89
	v_max_f32_e32 v111, v112, v109
	v_min_f32_e32 v109, v112, v109
	v_max_f32_e32 v112, v90, v113
	v_min_f32_e32 v90, v90, v113
	v_max_f32_e32 v113, v110, v86
	v_min_f32_e32 v86, v110, v86
	v_max_f32_e32 v110, v85, v91
	v_min_f32_e32 v85, v85, v91
	v_max_f32_e32 v91, v87, v88
	v_min_f32_e32 v87, v87, v88
	v_max_f32_e32 v88, v82, v80
	v_min_f32_e32 v80, v82, v80
	v_max_f32_e32 v114, v83, v111
	v_min_f32_e32 v111, v83, v111
	v_max_f32_e32 v115, v84, v112
	v_min_f32_e32 v112, v84, v112
	v_max_f32_e32 v116, v81, v109
	v_min_f32_e32 v109, v81, v109
	v_max_f32_e32 v117, v89, v90
	v_min_f32_e32 v89, v89, v90
	v_max_f32_e32 v90, v113, v91
	v_min_f32_e32 v91, v113, v91
	v_max_f32_e32 v113, v110, v88
	v_min_f32_e32 v88, v110, v88
	v_max_f32_e32 v110, v86, v87
	v_min_f32_e32 v118, v86, v87
	v_max_f32_e32 v119, v85, v80
	v_min_f32_e32 v120, v85, v80
	ds_read_b128 v[80:83], v107 offset:128
	ds_read_b128 v[84:87], v107 offset:144
	v_min_f32_e32 v121, v114, v115
	v_min_f32_e32 v123, v116, v117
	v_min_f32_e32 v125, v90, v113
	v_min_f32_e32 v122, v111, v112
	s_waitcnt vmcnt(2) lgkmcnt(1)
	v_fma_f32 v68, v80, v106, v68
	s_waitcnt lgkmcnt(0)
	v_fma_f32 v64, v84, v106, v64
	v_and_b32_e32 v68, 0xffffff80, v68
	v_and_b32_e32 v64, 0xffffff80, v64
	v_or3_b32 v80, v105, v68, 32
	v_fma_f32 v68, v81, v106, v69
	v_or3_b32 v84, v105, v64, 36
	v_fma_f32 v64, v85, v106, v65
	v_and_b32_e32 v68, 0xffffff80, v68
	v_and_b32_e32 v64, 0xffffff80, v64
	v_or3_b32 v81, v105, v68, 33
	v_fma_f32 v68, v82, v106, v70
	v_or3_b32 v85, v105, v64, 37
	v_fma_f32 v64, v86, v106, v66
	v_and_b32_e32 v68, 0xffffff80, v68
	v_fmac_f32_e32 v71, v83, v106
	v_and_b32_e32 v64, 0xffffff80, v64
	v_fmac_f32_e32 v67, v87, v106
	v_or3_b32 v82, v105, v68, 34
	v_and_b32_e32 v68, 0xffffff80, v71
	v_or3_b32 v86, v105, v64, 38
	v_and_b32_e32 v64, 0xffffff80, v67
	v_or3_b32 v83, v105, v68, 35
	ds_read_b128 v[68:71], v107 offset:160
	v_or3_b32 v87, v105, v64, 39
	ds_read_b128 v[64:67], v107 offset:176
	v_min_f32_e32 v124, v109, v89
	v_min_f32_e32 v126, v91, v88
	s_waitcnt vmcnt(0) lgkmcnt(1)
	v_fma_f32 v68, v68, v106, v76
	v_fma_f32 v69, v69, v106, v77
	s_waitcnt lgkmcnt(0)
	v_fma_f32 v64, v64, v106, v72
	v_fma_f32 v65, v65, v106, v73
	v_fmac_f32_e32 v75, v67, v106
	v_max_f32_e32 v72, v81, v81
	v_max_f32_e32 v73, v80, v80
	v_and_b32_e32 v68, 0xffffff80, v68
	v_and_b32_e32 v69, 0xffffff80, v69
	v_fma_f32 v70, v70, v106, v78
	v_fmac_f32_e32 v79, v71, v106
	v_fma_f32 v66, v66, v106, v74
	v_and_b32_e32 v67, 0xffffff80, v75
	v_max_f32_e32 v74, v73, v72
	v_min_f32_e32 v72, v73, v72
	v_max_f32_e32 v73, v82, v82
	v_max_f32_e32 v75, v83, v83
	v_or3_b32 v68, v105, v68, 40
	v_or3_b32 v69, v105, v69, 41
	v_and_b32_e32 v70, 0xffffff80, v70
	v_and_b32_e32 v71, 0xffffff80, v79
	v_and_b32_e32 v64, 0xffffff80, v64
	v_and_b32_e32 v65, 0xffffff80, v65
	v_max_f32_e32 v76, v75, v73
	v_min_f32_e32 v73, v75, v73
	v_max_f32_e32 v75, v85, v85
	v_max_f32_e32 v77, v84, v84
	v_or3_b32 v70, v105, v70, 42
	v_or3_b32 v71, v105, v71, 43
	v_or3_b32 v64, v105, v64, 44
	v_or3_b32 v65, v105, v65, 45
	v_and_b32_e32 v66, 0xffffff80, v66
	v_max_f32_e32 v78, v77, v75
	v_min_f32_e32 v75, v77, v75
	v_max_f32_e32 v77, v86, v86
	v_max_f32_e32 v79, v87, v87
	v_max_f32_e32 v69, v69, v69
	v_max_f32_e32 v68, v68, v68
	v_or3_b32 v66, v105, v66, 46
	v_or3_b32 v67, v105, v67, 47
	v_max_f32_e32 v80, v79, v77
	v_min_f32_e32 v77, v79, v77
	v_max_f32_e32 v79, v68, v69
	v_min_f32_e32 v68, v68, v69
	v_max_f32_e32 v69, v70, v70
	v_max_f32_e32 v70, v71, v71
	v_max_f32_e32 v65, v65, v65
	v_max_f32_e32 v64, v64, v64
	v_max_f32_e32 v71, v70, v69
	v_min_f32_e32 v69, v70, v69
	v_max_f32_e32 v70, v64, v65
	v_min_f32_e32 v64, v64, v65
	v_max_f32_e32 v65, v66, v66
	v_max_f32_e32 v66, v67, v67
	v_max_f32_e32 v67, v66, v65
	v_min_f32_e32 v65, v66, v65
	v_max_f32_e32 v66, v74, v73
	v_min_f32_e32 v73, v74, v73
	v_max_f32_e32 v74, v72, v76
	v_min_f32_e32 v72, v72, v76
	v_max_f32_e32 v76, v77, v78
	v_min_f32_e32 v77, v77, v78
	v_max_f32_e32 v78, v80, v75
	v_min_f32_e32 v75, v80, v75
	v_max_f32_e32 v80, v79, v69
	v_min_f32_e32 v69, v79, v69
	v_max_f32_e32 v79, v68, v71
	v_min_f32_e32 v68, v68, v71
	v_max_f32_e32 v71, v65, v70
	v_min_f32_e32 v65, v65, v70
	v_max_f32_e32 v70, v67, v64
	v_min_f32_e32 v64, v67, v64
	v_max_f32_e32 v67, v66, v74
	v_min_f32_e32 v66, v66, v74
	v_max_f32_e32 v74, v73, v72
	v_min_f32_e32 v72, v73, v72
	v_max_f32_e32 v73, v75, v77
	v_min_f32_e32 v75, v75, v77
	v_max_f32_e32 v77, v78, v76
	v_min_f32_e32 v76, v78, v76
	v_max_f32_e32 v78, v80, v79
	v_min_f32_e32 v79, v80, v79
	v_max_f32_e32 v80, v69, v68
	v_min_f32_e32 v68, v69, v68
	v_max_f32_e32 v69, v64, v65
	v_min_f32_e32 v64, v64, v65
	v_max_f32_e32 v65, v70, v71
	v_min_f32_e32 v70, v70, v71
	v_max_f32_e32 v71, v67, v75
	v_min_f32_e32 v67, v67, v75
	v_max_f32_e32 v75, v66, v73
	v_min_f32_e32 v66, v66, v73
	v_max_f32_e32 v73, v74, v76
	v_min_f32_e32 v74, v74, v76
	v_max_f32_e32 v76, v72, v77
	v_min_f32_e32 v72, v72, v77
	v_max_f32_e32 v77, v64, v78
	v_min_f32_e32 v64, v64, v78
	v_max_f32_e32 v78, v69, v79
	v_min_f32_e32 v69, v69, v79
	v_max_f32_e32 v79, v70, v80
	v_min_f32_e32 v70, v70, v80
	v_max_f32_e32 v80, v65, v68
	v_min_f32_e32 v65, v65, v68
	v_max_f32_e32 v68, v71, v73
	v_min_f32_e32 v71, v71, v73
	v_max_f32_e32 v73, v75, v76
	v_min_f32_e32 v75, v75, v76
	v_max_f32_e32 v76, v67, v74
	v_min_f32_e32 v67, v67, v74
	v_max_f32_e32 v74, v66, v72
	v_min_f32_e32 v66, v66, v72
	v_max_f32_e32 v72, v70, v64
	v_min_f32_e32 v64, v70, v64
	v_max_f32_e32 v70, v65, v69
	v_min_f32_e32 v65, v65, v69
	v_max_f32_e32 v69, v79, v77
	v_min_f32_e32 v77, v79, v77
	v_max_f32_e32 v79, v80, v78
	v_min_f32_e32 v78, v80, v78
	v_max_f32_e32 v80, v68, v73
	v_min_f32_e32 v68, v68, v73
	v_max_f32_e32 v73, v71, v75
	v_min_f32_e32 v71, v71, v75
	v_max_f32_e32 v75, v76, v74
	v_min_f32_e32 v74, v76, v74
	v_max_f32_e32 v76, v67, v66
	v_min_f32_e32 v66, v67, v66
	v_max_f32_e32 v67, v65, v64
	v_min_f32_e32 v64, v65, v64
	v_max_f32_e32 v65, v70, v72
	v_min_f32_e32 v70, v70, v72
	v_max_f32_e32 v72, v78, v77
	v_min_f32_e32 v77, v78, v77
	v_max_f32_e32 v78, v79, v69
	v_min_f32_e32 v69, v79, v69
	v_max_f32_e32 v79, v80, v64
	v_min_f32_e32 v64, v80, v64
	v_max_f32_e32 v80, v68, v67
	v_min_f32_e32 v67, v68, v67
	v_max_f32_e32 v68, v73, v70
	v_min_f32_e32 v70, v73, v70
	v_max_f32_e32 v73, v71, v65
	v_min_f32_e32 v65, v71, v65
	v_max_f32_e32 v71, v75, v77
	v_min_f32_e32 v75, v75, v77
	v_max_f32_e32 v77, v74, v72
	v_min_f32_e32 v72, v74, v72
	v_max_f32_e32 v74, v76, v69
	v_min_f32_e32 v69, v76, v69
	v_max_f32_e32 v76, v66, v78
	v_min_f32_e32 v66, v66, v78
	v_max_f32_e32 v78, v79, v71
	v_min_f32_e32 v71, v79, v71
	v_max_f32_e32 v79, v80, v77
	v_min_f32_e32 v77, v80, v77
	v_max_f32_e32 v80, v68, v74
	v_min_f32_e32 v68, v68, v74
	v_max_f32_e32 v74, v73, v76
	v_min_f32_e32 v73, v73, v76
	v_max_f32_e32 v76, v64, v75
	v_min_f32_e32 v64, v64, v75
	v_max_f32_e32 v75, v67, v72
	v_min_f32_e32 v67, v67, v72
	v_max_f32_e32 v72, v70, v69
	v_min_f32_e32 v69, v70, v69
	v_max_f32_e32 v70, v65, v66
	v_min_f32_e32 v65, v65, v66
	v_max_f32_e32 v81, v78, v80
	v_min_f32_e32 v78, v78, v80
	v_max_f32_e32 v80, v79, v74
	v_min_f32_e32 v74, v79, v74
	v_max_f32_e32 v79, v71, v68
	v_min_f32_e32 v82, v71, v68
	v_max_f32_e32 v83, v77, v73
	v_min_f32_e32 v73, v77, v73
	v_max_f32_e32 v77, v76, v72
	v_min_f32_e32 v72, v76, v72
	v_max_f32_e32 v76, v75, v70
	v_min_f32_e32 v75, v75, v70
	v_max_f32_e32 v84, v64, v69
	v_min_f32_e32 v85, v64, v69
	v_max_f32_e32 v86, v67, v65
	v_min_f32_e32 v87, v67, v65
	global_load_dwordx4 v[64:67], v108, s[50:51] offset:208
	global_load_dwordx4 v[68:71], v108, s[50:51] offset:192
	v_min_f32_e32 v133, v82, v73
	v_min_f32_e32 v137, v84, v86
	v_min_f32_e32 v138, v85, v87
	v_min_f32_e32 v127, v110, v119
	v_min_f32_e32 v128, v118, v120
	v_min_f32_e32 v131, v78, v74
	v_min_f32_e32 v132, v79, v83
	v_min_f32_e32 v135, v77, v76
	v_min_f32_e32 v136, v72, v75
	v_max3_f32 v114, v114, v115, v138
	v_max3_f32 v85, v121, v85, v87
	v_max3_f32 v87, v111, v112, v137
	v_max3_f32 v111, v123, v72, v75
	v_max3_f32 v72, v90, v113, v133
	v_max3_f32 v73, v125, v82, v73
	v_min_f32_e32 v130, v81, v80
	v_max3_f32 v89, v109, v89, v135
	v_max3_f32 v109, v124, v77, v76
	v_max3_f32 v82, v91, v88, v132
	v_max3_f32 v83, v126, v79, v83
	v_max3_f32 v88, v110, v119, v131
	v_max3_f32 v90, v127, v78, v74
	v_max3_f32 v80, v128, v81, v80
	v_max_f32_e32 v81, v114, v72
	v_min_f32_e32 v110, v114, v72
	v_max_f32_e32 v112, v85, v73
	v_min_f32_e32 v85, v85, v73
	global_load_dwordx4 v[72:75], v108, s[50:51] offset:240
	global_load_dwordx4 v[76:79], v108, s[50:51] offset:224
	v_max3_f32 v84, v122, v84, v86
	v_max3_f32 v86, v116, v117, v136
	v_max3_f32 v91, v118, v120, v130
	v_max_f32_e32 v113, v87, v82
	v_min_f32_e32 v82, v87, v82
	v_max_f32_e32 v87, v84, v83
	v_min_f32_e32 v83, v84, v83
	v_max_f32_e32 v84, v86, v88
	v_min_f32_e32 v86, v86, v88
	v_max_f32_e32 v88, v111, v90
	v_min_f32_e32 v90, v111, v90
	v_max_f32_e32 v108, v89, v91
	v_min_f32_e32 v89, v89, v91
	v_max_f32_e32 v91, v109, v80
	v_min_f32_e32 v80, v109, v80
	v_max_f32_e32 v109, v81, v84
	v_min_f32_e32 v81, v81, v84
	v_max_f32_e32 v84, v112, v88
	v_min_f32_e32 v88, v112, v88
	v_max_f32_e32 v111, v113, v108
	v_min_f32_e32 v108, v113, v108
	v_max_f32_e32 v112, v87, v91
	v_min_f32_e32 v87, v87, v91
	v_max_f32_e32 v91, v110, v86
	v_min_f32_e32 v86, v110, v86
	v_max_f32_e32 v110, v85, v90
	v_min_f32_e32 v85, v85, v90
	v_max_f32_e32 v90, v82, v89
	v_min_f32_e32 v82, v82, v89
	v_max_f32_e32 v89, v83, v80
	v_min_f32_e32 v80, v83, v80
	v_max_f32_e32 v113, v109, v111
	v_min_f32_e32 v109, v109, v111
	v_max_f32_e32 v111, v84, v112
	v_min_f32_e32 v112, v84, v112
	v_max_f32_e32 v114, v81, v108
	v_min_f32_e32 v108, v81, v108
	v_max_f32_e32 v115, v88, v87
	v_min_f32_e32 v88, v88, v87
	v_max_f32_e32 v116, v91, v90
	v_min_f32_e32 v90, v91, v90
	v_max_f32_e32 v91, v110, v89
	v_min_f32_e32 v89, v110, v89
	v_max_f32_e32 v110, v86, v82
	v_min_f32_e32 v117, v86, v82
	v_max_f32_e32 v118, v85, v80
	v_min_f32_e32 v119, v85, v80
	ds_read_b128 v[80:83], v107 offset:192
	ds_read_b128 v[84:87], v107 offset:208
	v_min_f32_e32 v120, v113, v111
	v_min_f32_e32 v121, v109, v112
	v_min_f32_e32 v122, v114, v115
	s_waitcnt vmcnt(2) lgkmcnt(1)
	v_fma_f32 v68, v80, v106, v68
	s_waitcnt lgkmcnt(0)
	v_fma_f32 v64, v84, v106, v64
	v_and_b32_e32 v68, 0xffffff80, v68
	v_and_b32_e32 v64, 0xffffff80, v64
	v_or3_b32 v80, v105, v68, 48
	v_fma_f32 v68, v81, v106, v69
	v_or3_b32 v84, v105, v64, 52
	v_fma_f32 v64, v85, v106, v65
	v_and_b32_e32 v68, 0xffffff80, v68
	v_and_b32_e32 v64, 0xffffff80, v64
	v_or3_b32 v81, v105, v68, 49
	v_fma_f32 v68, v82, v106, v70
	v_or3_b32 v85, v105, v64, 53
	v_fma_f32 v64, v86, v106, v66
	v_and_b32_e32 v68, 0xffffff80, v68
	v_fmac_f32_e32 v71, v83, v106
	v_and_b32_e32 v64, 0xffffff80, v64
	v_fmac_f32_e32 v67, v87, v106
	v_or3_b32 v82, v105, v68, 50
	v_and_b32_e32 v68, 0xffffff80, v71
	v_or3_b32 v86, v105, v64, 54
	v_and_b32_e32 v64, 0xffffff80, v67
	v_or3_b32 v83, v105, v68, 51
	ds_read_b128 v[68:71], v107 offset:224
	v_or3_b32 v87, v105, v64, 55
	ds_read_b128 v[64:67], v107 offset:240
	v_min_f32_e32 v123, v108, v88
	v_min_f32_e32 v124, v116, v91
	s_waitcnt vmcnt(0) lgkmcnt(1)
	v_fma_f32 v68, v68, v106, v76
	v_fma_f32 v69, v69, v106, v77
	s_waitcnt lgkmcnt(0)
	v_fma_f32 v64, v64, v106, v72
	v_fma_f32 v65, v65, v106, v73
	v_fmac_f32_e32 v75, v67, v106
	v_max_f32_e32 v72, v81, v81
	v_max_f32_e32 v73, v80, v80
	v_and_b32_e32 v68, 0xffffff80, v68
	v_and_b32_e32 v69, 0xffffff80, v69
	v_fma_f32 v70, v70, v106, v78
	v_fmac_f32_e32 v79, v71, v106
	v_fma_f32 v66, v66, v106, v74
	v_and_b32_e32 v67, 0xffffff80, v75
	v_max_f32_e32 v74, v73, v72
	v_min_f32_e32 v72, v73, v72
	v_max_f32_e32 v73, v82, v82
	v_max_f32_e32 v75, v83, v83
	v_or3_b32 v68, v105, v68, 56
	v_or3_b32 v69, v105, v69, 57
	v_and_b32_e32 v70, 0xffffff80, v70
	v_and_b32_e32 v71, 0xffffff80, v79
	v_and_b32_e32 v64, 0xffffff80, v64
	v_and_b32_e32 v65, 0xffffff80, v65
	v_max_f32_e32 v76, v75, v73
	v_min_f32_e32 v73, v75, v73
	v_max_f32_e32 v75, v85, v85
	v_max_f32_e32 v77, v84, v84
	v_or3_b32 v70, v105, v70, 58
	v_or3_b32 v71, v105, v71, 59
	v_or3_b32 v64, v105, v64, 60
	v_or3_b32 v65, v105, v65, 61
	v_and_b32_e32 v66, 0xffffff80, v66
	v_max_f32_e32 v78, v77, v75
	v_min_f32_e32 v75, v77, v75
	v_max_f32_e32 v77, v86, v86
	v_max_f32_e32 v79, v87, v87
	v_max_f32_e32 v69, v69, v69
	v_max_f32_e32 v68, v68, v68
	v_or3_b32 v66, v105, v66, 62
	v_or3_b32 v67, v105, v67, 63
	v_max_f32_e32 v80, v79, v77
	v_min_f32_e32 v77, v79, v77
	v_max_f32_e32 v79, v68, v69
	v_min_f32_e32 v68, v68, v69
	v_max_f32_e32 v69, v70, v70
	v_max_f32_e32 v70, v71, v71
	v_max_f32_e32 v65, v65, v65
	v_max_f32_e32 v64, v64, v64
	v_max_f32_e32 v71, v70, v69
	v_min_f32_e32 v69, v70, v69
	v_max_f32_e32 v70, v64, v65
	v_min_f32_e32 v64, v64, v65
	v_max_f32_e32 v65, v66, v66
	v_max_f32_e32 v66, v67, v67
	v_max_f32_e32 v67, v66, v65
	v_min_f32_e32 v65, v66, v65
	v_max_f32_e32 v66, v74, v73
	v_min_f32_e32 v73, v74, v73
	v_max_f32_e32 v74, v72, v76
	v_min_f32_e32 v72, v72, v76
	v_max_f32_e32 v76, v77, v78
	v_min_f32_e32 v77, v77, v78
	v_max_f32_e32 v78, v80, v75
	v_min_f32_e32 v75, v80, v75
	v_max_f32_e32 v80, v79, v69
	v_min_f32_e32 v69, v79, v69
	v_max_f32_e32 v79, v68, v71
	v_min_f32_e32 v68, v68, v71
	v_max_f32_e32 v71, v65, v70
	v_min_f32_e32 v65, v65, v70
	v_max_f32_e32 v70, v67, v64
	v_min_f32_e32 v64, v67, v64
	v_max_f32_e32 v67, v66, v74
	v_min_f32_e32 v66, v66, v74
	v_max_f32_e32 v74, v73, v72
	v_min_f32_e32 v72, v73, v72
	v_max_f32_e32 v73, v75, v77
	v_min_f32_e32 v75, v75, v77
	v_max_f32_e32 v77, v78, v76
	v_min_f32_e32 v76, v78, v76
	v_max_f32_e32 v78, v80, v79
	v_min_f32_e32 v79, v80, v79
	v_max_f32_e32 v80, v69, v68
	v_min_f32_e32 v68, v69, v68
	v_max_f32_e32 v69, v64, v65
	v_min_f32_e32 v64, v64, v65
	v_max_f32_e32 v65, v70, v71
	v_min_f32_e32 v70, v70, v71
	v_max_f32_e32 v71, v67, v75
	v_min_f32_e32 v67, v67, v75
	v_max_f32_e32 v75, v66, v73
	v_min_f32_e32 v66, v66, v73
	v_max_f32_e32 v73, v74, v76
	v_min_f32_e32 v74, v74, v76
	v_max_f32_e32 v76, v72, v77
	v_min_f32_e32 v72, v72, v77
	v_max_f32_e32 v77, v64, v78
	v_min_f32_e32 v64, v64, v78
	v_max_f32_e32 v78, v69, v79
	v_min_f32_e32 v69, v69, v79
	v_max_f32_e32 v79, v70, v80
	v_min_f32_e32 v70, v70, v80
	v_max_f32_e32 v80, v65, v68
	v_min_f32_e32 v65, v65, v68
	v_max_f32_e32 v68, v71, v73
	v_min_f32_e32 v71, v71, v73
	v_max_f32_e32 v73, v75, v76
	v_min_f32_e32 v75, v75, v76
	v_max_f32_e32 v76, v67, v74
	v_min_f32_e32 v67, v67, v74
	v_max_f32_e32 v74, v66, v72
	v_min_f32_e32 v66, v66, v72
	v_max_f32_e32 v72, v70, v64
	v_min_f32_e32 v64, v70, v64
	v_max_f32_e32 v70, v65, v69
	v_min_f32_e32 v65, v65, v69
	v_max_f32_e32 v69, v79, v77
	v_min_f32_e32 v77, v79, v77
	v_max_f32_e32 v79, v80, v78
	v_min_f32_e32 v78, v80, v78
	v_max_f32_e32 v80, v68, v73
	v_min_f32_e32 v68, v68, v73
	v_max_f32_e32 v73, v71, v75
	v_min_f32_e32 v71, v71, v75
	v_max_f32_e32 v75, v76, v74
	v_min_f32_e32 v74, v76, v74
	v_max_f32_e32 v76, v67, v66
	v_min_f32_e32 v66, v67, v66
	v_max_f32_e32 v67, v65, v64
	v_min_f32_e32 v64, v65, v64
	v_max_f32_e32 v65, v70, v72
	v_min_f32_e32 v70, v70, v72
	v_max_f32_e32 v72, v78, v77
	v_min_f32_e32 v77, v78, v77
	v_max_f32_e32 v78, v79, v69
	v_min_f32_e32 v69, v79, v69
	v_max_f32_e32 v79, v80, v64
	v_min_f32_e32 v64, v80, v64
	v_max_f32_e32 v80, v68, v67
	v_min_f32_e32 v67, v68, v67
	v_max_f32_e32 v68, v73, v70
	v_min_f32_e32 v70, v73, v70
	v_max_f32_e32 v73, v71, v65
	v_min_f32_e32 v65, v71, v65
	v_max_f32_e32 v71, v75, v77
	v_min_f32_e32 v75, v75, v77
	v_max_f32_e32 v77, v74, v72
	v_min_f32_e32 v72, v74, v72
	v_max_f32_e32 v74, v76, v69
	v_min_f32_e32 v69, v76, v69
	v_max_f32_e32 v76, v66, v78
	v_min_f32_e32 v66, v66, v78
	v_max_f32_e32 v78, v79, v71
	v_min_f32_e32 v71, v79, v71
	v_max_f32_e32 v79, v80, v77
	v_min_f32_e32 v77, v80, v77
	v_max_f32_e32 v80, v68, v74
	v_min_f32_e32 v68, v68, v74
	v_max_f32_e32 v74, v73, v76
	v_min_f32_e32 v73, v73, v76
	v_max_f32_e32 v76, v64, v75
	v_min_f32_e32 v64, v64, v75
	v_max_f32_e32 v75, v67, v72
	v_min_f32_e32 v67, v67, v72
	v_max_f32_e32 v72, v70, v69
	v_min_f32_e32 v69, v70, v69
	v_max_f32_e32 v70, v65, v66
	v_min_f32_e32 v65, v65, v66
	v_max_f32_e32 v66, v78, v80
	v_min_f32_e32 v78, v78, v80
	v_max_f32_e32 v80, v79, v74
	v_min_f32_e32 v74, v79, v74
	v_max_f32_e32 v79, v71, v68
	v_min_f32_e32 v68, v71, v68
	v_max_f32_e32 v71, v77, v73
	v_min_f32_e32 v73, v77, v73
	v_max_f32_e32 v77, v76, v72
	v_min_f32_e32 v72, v76, v72
	v_max_f32_e32 v76, v75, v70
	v_min_f32_e32 v70, v75, v70
	v_max_f32_e32 v75, v64, v69
	v_min_f32_e32 v64, v64, v69
	v_max_f32_e32 v69, v67, v65
	v_min_f32_e32 v65, v67, v65
	v_min_f32_e32 v125, v90, v89
	v_min_f32_e32 v126, v110, v118
	v_min_f32_e32 v127, v117, v119
	v_min_f32_e32 v67, v66, v80
	v_min_f32_e32 v81, v78, v74
	v_min_f32_e32 v82, v79, v71
	v_min_f32_e32 v83, v68, v73
	v_min_f32_e32 v84, v77, v76
	v_min_f32_e32 v85, v72, v70
	v_min_f32_e32 v86, v75, v69
	v_min_f32_e32 v87, v64, v65
	v_max3_f32 v87, v113, v111, v87
	v_max3_f32 v83, v116, v91, v83
	v_max3_f32 v85, v114, v115, v85
	v_max3_f32 v81, v110, v118, v81
	v_max3_f32 v86, v109, v112, v86
	v_max3_f32 v82, v90, v89, v82
	v_max3_f32 v84, v108, v88, v84
	v_max3_f32 v67, v117, v119, v67
	v_max3_f32 v64, v120, v64, v65
	v_max3_f32 v65, v124, v68, v73
	v_max3_f32 v70, v122, v72, v70
	v_max3_f32 v72, v126, v78, v74
	v_max3_f32 v69, v121, v75, v69
	v_max3_f32 v71, v125, v79, v71
	v_max3_f32 v76, v123, v77, v76
	v_max3_f32 v66, v127, v66, v80
	v_min_f32_e32 v105, v85, v81
	v_min_f32_e32 v89, v86, v82
	v_min_f32_e32 v88, v84, v67
	v_min_f32_e32 v68, v64, v65
	v_min_f32_e32 v75, v69, v71
	v_min_f32_e32 v77, v76, v66
	v_max_f32_e32 v80, v87, v83
	v_max_f32_e32 v81, v85, v81
	v_max_f32_e32 v82, v86, v82
	v_max_f32_e32 v67, v84, v67
	v_max_f32_e32 v64, v64, v65
	v_max_f32_e32 v65, v70, v72
	v_max_f32_e32 v69, v69, v71
	v_max_f32_e32 v66, v76, v66
	v_min_f32_e32 v91, v87, v83
	v_min_f32_e32 v73, v70, v72
	v_max_f32_e32 v83, v80, v81
	v_max_f32_e32 v84, v82, v67
	v_max_f32_e32 v70, v64, v65
	v_max_f32_e32 v71, v69, v66
	v_max_f32_e32 v85, v83, v84
	v_max_f32_e32 v72, v70, v71
	v_max_f32_e32 v109, v85, v72
	v_min_f32_e32 v86, v85, v72
	v_min_f32_e32 v72, v83, v84
	v_min_f32_e32 v70, v70, v71
	v_max_f32_e32 v71, v72, v70
	v_min_f32_e32 v70, v72, v70
	v_min_f32_e32 v72, v80, v81
	v_min_f32_e32 v67, v82, v67
	v_min_f32_e32 v64, v64, v65
	v_min_f32_e32 v65, v69, v66
	v_max_f32_e32 v76, v72, v67
	v_max_f32_e32 v66, v64, v65
	v_min_f32_e32 v67, v72, v67
	v_min_f32_e32 v64, v64, v65
	v_min_f32_e32 v74, v68, v73
	v_max_f32_e32 v65, v67, v64
	v_min_f32_e32 v64, v67, v64
	v_max_f32_e32 v67, v91, v105
	v_max_f32_e32 v72, v89, v88
	v_max_f32_e32 v68, v68, v73
	v_max_f32_e32 v73, v75, v77
	v_min_f32_e32 v78, v75, v77
	v_max_f32_e32 v69, v76, v66
	v_min_f32_e32 v66, v76, v66
	v_max_f32_e32 v76, v67, v72
	v_max_f32_e32 v75, v68, v73
	v_min_f32_e32 v67, v67, v72
	v_min_f32_e32 v68, v68, v73
	v_min_f32_e32 v79, v74, v78
	v_max_f32_e32 v83, v67, v68
	v_min_f32_e32 v67, v67, v68
	v_max_f32_e32 v72, v74, v78
	v_mov_b32_e32 v74, v129
	v_max_f32_e32 v81, v76, v75
	v_min_f32_e32 v82, v76, v75
	v_mov_b32_dpp v74, v67 quad_perm:[1,0,3,2] row_mask:0xf bank_mask:0xf
	v_max_f32_e32 v74, v74, v74
	v_max_f32_e32 v80, v69, v74
	v_mov_b32_e32 v74, v129
	v_min_f32_e32 v106, v91, v105
	v_min_f32_e32 v90, v89, v88
	v_mov_b32_dpp v74, v83 quad_perm:[1,0,3,2] row_mask:0xf bank_mask:0xf
	v_max_f32_e32 v74, v74, v74
	v_max_f32_e32 v75, v66, v74
	v_mov_b32_e32 v74, v129
	v_min_f32_e32 v107, v106, v90
	v_min_f32_e32 v108, v107, v79
	v_mov_b32_dpp v74, v82 quad_perm:[1,0,3,2] row_mask:0xf bank_mask:0xf
	v_max_f32_e32 v74, v74, v74
	v_max_f32_e32 v78, v65, v74
	v_mov_b32_e32 v74, v129
	v_max_f32_e32 v88, v107, v79
	v_mov_b32_e32 v79, v129
	v_mov_b32_dpp v74, v81 quad_perm:[1,0,3,2] row_mask:0xf bank_mask:0xf
	v_max_f32_e32 v74, v74, v74
	v_mov_b32_dpp v79, v64 quad_perm:[1,0,3,2] row_mask:0xf bank_mask:0xf
	v_max_f32_e32 v74, v64, v74
	v_max_f32_e32 v64, v79, v79
	v_max_f32_e32 v85, v81, v64
	v_mov_b32_e32 v64, v129
	v_max_f32_e32 v68, v106, v90
	v_max_f32_e32 v87, v68, v72
	v_mov_b32_dpp v64, v65 quad_perm:[1,0,3,2] row_mask:0xf bank_mask:0xf
	v_min_f32_e32 v68, v68, v72
	v_mov_b32_e32 v72, v129
	v_max_f32_e32 v64, v64, v64
	v_max_f32_e32 v81, v82, v64
	v_mov_b32_dpp v72, v108 quad_perm:[1,0,3,2] row_mask:0xf bank_mask:0xf
	v_mov_b32_e32 v64, v129
	v_max_f32_e32 v72, v72, v72
	v_max_f32_e32 v77, v109, v72
	v_mov_b32_dpp v64, v66 quad_perm:[1,0,3,2] row_mask:0xf bank_mask:0xf
	v_mov_b32_e32 v72, v129
	v_max_f32_e32 v64, v64, v64
	v_max_f32_e32 v84, v83, v64
	v_mov_b32_dpp v72, v88 quad_perm:[1,0,3,2] row_mask:0xf bank_mask:0xf
	v_mov_b32_e32 v64, v129
	v_max_f32_e32 v72, v72, v72
	v_max_f32_e32 v73, v86, v72
	v_mov_b32_dpp v64, v69 quad_perm:[1,0,3,2] row_mask:0xf bank_mask:0xf
	v_mov_b32_e32 v72, v129
	v_max_f32_e32 v64, v64, v64
	v_max_f32_e32 v79, v67, v64
	v_mov_b32_dpp v72, v68 quad_perm:[1,0,3,2] row_mask:0xf bank_mask:0xf
	v_mov_b32_e32 v64, v129
	v_max_f32_e32 v72, v72, v72
	v_max_f32_e32 v76, v71, v72
	v_mov_b32_dpp v64, v70 quad_perm:[1,0,3,2] row_mask:0xf bank_mask:0xf
	v_mov_b32_e32 v72, v129
	v_max_f32_e32 v64, v64, v64
	s_nop 0
	v_mov_b32_dpp v72, v87 quad_perm:[1,0,3,2] row_mask:0xf bank_mask:0xf
	v_max_f32_e32 v87, v87, v64
	v_mov_b32_e32 v64, v129
	v_max_f32_e32 v72, v72, v72
	v_max_f32_e32 v72, v70, v72
	v_mov_b32_dpp v64, v71 quad_perm:[1,0,3,2] row_mask:0xf bank_mask:0xf
	v_max_f32_e32 v64, v64, v64
	v_max_f32_e32 v83, v68, v64
	v_mov_b32_e32 v64, v129
	s_nop 1
	v_mov_b32_dpp v64, v86 quad_perm:[1,0,3,2] row_mask:0xf bank_mask:0xf
	v_max_f32_e32 v64, v64, v64
	v_max_f32_e32 v86, v88, v64
	v_mov_b32_e32 v64, v129
	s_nop 1
	v_mov_b32_dpp v64, v109 quad_perm:[1,0,3,2] row_mask:0xf bank_mask:0xf
	v_max_f32_e32 v64, v64, v64
	v_max_f32_e32 v82, v108, v64
	s_and_saveexec_b64 s[52:53], vcc
	s_xor_b64 s[52:53], exec, s[52:53]
	s_cbranch_execz .LBB0_701
	v_max_f32_e32 v64, v85, v85
	v_max_f32_e32 v65, v77, v77
	v_max_f32_e32 v67, v81, v81
	v_max_f32_e32 v73, v73, v73
	v_min_f32_e32 v68, v65, v64
	v_max_f32_e32 v64, v87, v87
	v_max_f32_e32 v65, v80, v80
	v_min_f32_e32 v73, v73, v67
	v_max_f32_e32 v67, v83, v83
	v_max_f32_e32 v75, v75, v75
	v_min_f32_e32 v69, v65, v64
	v_max_f32_e32 v65, v84, v84
	v_max_f32_e32 v66, v76, v76
	v_min_f32_e32 v75, v75, v67
	v_max_f32_e32 v67, v79, v79
	v_max_f32_e32 v72, v72, v72
	v_min_f32_e32 v70, v66, v65
	v_max_f32_e32 v65, v86, v86
	v_max_f32_e32 v66, v78, v78
	v_min_f32_e32 v72, v72, v67
	v_max_f32_e32 v67, v82, v82
	v_max_f32_e32 v74, v74, v74
	v_min_f32_e32 v71, v66, v65
	v_min_f32_e32 v74, v74, v67
	v_min_f32_e32 v64, v68, v69
	v_min_f32_e32 v65, v70, v71
	v_min_f32_e32 v76, v73, v75
	v_min_f32_e32 v77, v72, v74
	v_max_f32_e32 v68, v68, v69
	v_max_f32_e32 v69, v70, v71
	v_max_f32_e32 v73, v73, v75
	v_max_f32_e32 v72, v72, v74
	v_min_f32_e32 v66, v64, v65
	v_min_f32_e32 v78, v76, v77
	v_max_f32_e32 v64, v64, v65
	v_max_f32_e32 v76, v76, v77
	v_min_f32_e32 v70, v68, v69
	v_min_f32_e32 v74, v73, v72
	v_max_f32_e32 v68, v68, v69
	v_max_f32_e32 v72, v73, v72
	v_min_f32_e32 v67, v66, v78
	v_max_f32_e32 v66, v66, v78
	v_min_f32_e32 v65, v64, v76
	v_max_f32_e32 v64, v64, v76
	v_min_f32_e32 v71, v70, v74
	v_max_f32_e32 v70, v70, v74
	v_min_f32_e32 v69, v68, v72
	v_max_f32_e32 v68, v68, v72

	.amdhsa_kernel _Z4mega6Params
		.amdhsa_group_segment_fixed_size 0
		.amdhsa_private_segment_fixed_size 0
		.amdhsa_kernarg_size 424
		.amdhsa_user_sgpr_count 2
		.amdhsa_user_sgpr_dispatch_ptr 0
		.amdhsa_user_sgpr_queue_ptr 0
		.amdhsa_user_sgpr_kernarg_segment_ptr 1
		.amdhsa_user_sgpr_dispatch_id 0
		.amdhsa_user_sgpr_kernarg_preload_length 0
		.amdhsa_user_sgpr_kernarg_preload_offset 0
		.amdhsa_user_sgpr_private_segment_size 0
		.amdhsa_uses_dynamic_stack 0
		.amdhsa_enable_private_segment 0
		.amdhsa_system_sgpr_workgroup_id_x 1
		.amdhsa_system_sgpr_workgroup_id_y 0
		.amdhsa_system_sgpr_workgroup_id_z 0
		.amdhsa_system_sgpr_workgroup_info 0
		.amdhsa_system_vgpr_workitem_id 2
		.amdhsa_next_free_vgpr 256
		.amdhsa_next_free_sgpr 102
		.amdhsa_accum_offset 256
		.amdhsa_reserve_vcc 1
		.amdhsa_float_round_mode_32 0
		.amdhsa_float_round_mode_16_64 0
		.amdhsa_float_denorm_mode_32 3
		.amdhsa_float_denorm_mode_16_64 3
		.amdhsa_dx10_clamp 1
		.amdhsa_ieee_mode 1
		.amdhsa_fp16_overflow 0
		.amdhsa_tg_split 0
		.amdhsa_exception_fp_ieee_invalid_op 0
		.amdhsa_exception_fp_denorm_src 0
		.amdhsa_exception_fp_ieee_div_zero 0
		.amdhsa_exception_fp_ieee_overflow 0
		.amdhsa_exception_fp_ieee_underflow 0
		.amdhsa_exception_fp_ieee_inexact 0
		.amdhsa_exception_int_div_zero 0
	.end_amdhsa_kernel

amdhsa.kernels:
  - .agpr_count:     0
    .args:
      - .offset:         0
        .size:           168
        .value_kind:     by_value
      - .offset:         168
        .size:           4
        .value_kind:     hidden_block_count_x
      - .offset:         172
        .size:           4
        .value_kind:     hidden_block_count_y
      - .offset:         176
        .size:           4
        .value_kind:     hidden_block_count_z
      - .offset:         180
        .size:           2
        .value_kind:     hidden_group_size_x
      - .offset:         182
        .size:           2
        .value_kind:     hidden_group_size_y
      - .offset:         184
        .size:           2
        .value_kind:     hidden_group_size_z
      - .offset:         186
        .size:           2
        .value_kind:     hidden_remainder_x
      - .offset:         188
        .size:           2
        .value_kind:     hidden_remainder_y
      - .offset:         190
        .size:           2
        .value_kind:     hidden_remainder_z
      - .offset:         208
        .size:           8
        .value_kind:     hidden_global_offset_x
      - .offset:         216
        .size:           8
        .value_kind:     hidden_global_offset_y
      - .offset:         224
        .size:           8
        .value_kind:     hidden_global_offset_z
      - .offset:         232
        .size:           2
        .value_kind:     hidden_grid_dims
      - .offset:         256
        .size:           8
        .value_kind:     hidden_multigrid_sync_arg
      - .offset:         288
        .size:           4
        .value_kind:     hidden_dynamic_lds_size
    .group_segment_fixed_size: 0
    .kernarg_segment_align: 8
    .kernarg_segment_size: 424
    .language:       OpenCL C
    .language_version:
      - 2
      - 0
    .max_flat_workgroup_size: 512
    .name:           _Z4mega6Params
    .private_segment_fixed_size: 0
    .sgpr_count:     108
    .sgpr_spill_count: 8
    .symbol:         _Z4mega6Params.kd
    .uniform_work_group_size: 1
    .uses_dynamic_stack: false
    .vgpr_count:     256
    .vgpr_spill_count: 0
    .wavefront_size: 64
